# epilogue rsqrt: removed never-taken denormal scaling around v_rsq_f32 in P1/P7/P9 epilogues (bit-identical), on top of v51
# speedup vs baseline: 1.0084x; 1.0006x over previous
.LBB0_510:
	s_and_b64 s[70:71], s[8:9], s[4:5]
	s_ashr_i32 s4, s76, 11
	s_mul_i32 s4, s65, s4
	s_add_i32 s4, s4, s63
	s_ashr_i32 s5, s4, 31
	v_lshl_add_u64 v[180:181], v[178:179], 0, v[152:153]
	s_lshl_b64 s[4:5], s[4:5], 18
	v_cndmask_b32_e64 v0, 0, 1, s[74:75]
	v_lshl_add_u64 v[182:183], v[180:181], 0, s[4:5]
	s_andn2_b64 vcc, exec, s[10:11]
	v_cmp_ne_u32_e64 s[10:11], 1, v0
	s_cbranch_vccnz .LBB0_517
	s_and_b64 vcc, exec, s[10:11]
	s_cbranch_vccnz .LBB0_632
	v_mul_f32_e32 v4, v17, v17
	v_fmac_f32_e32 v4, v16, v16
	v_fmac_f32_e32 v4, v18, v18
	v_fmac_f32_e32 v4, v19, v19
	v_fmac_f32_e32 v4, v20, v20
	v_fmac_f32_e32 v4, v21, v21
	v_fmac_f32_e32 v4, v22, v22
	v_fmac_f32_e32 v4, v23, v23
	v_pk_mul_f32 v[2:3], v[24:25], v[24:25]
	v_pk_mul_f32 v[0:1], v[26:27], v[26:27]
	v_add_f32_e32 v2, v2, v4
	v_add_f32_e32 v2, v3, v2
	v_add_f32_e32 v0, v0, v2
	v_add_f32_e32 v4, v1, v0
	v_pk_mul_f32 v[2:3], v[28:29], v[28:29]
	v_pk_mul_f32 v[0:1], v[30:31], v[30:31]
	v_add_f32_e32 v2, v2, v4
	v_add_f32_e32 v2, v3, v2
	v_add_f32_e32 v0, v0, v2
	v_add_f32_e32 v0, v1, v0
	ds_bpermute_b32 v1, v252, v0
	s_waitcnt lgkmcnt(0)
	v_add_f32_e32 v0, v0, v1
	ds_bpermute_b32 v1, v253, v0
	s_waitcnt lgkmcnt(0)
	v_add_f32_e32 v0, v0, v1
	s_waitcnt vmcnt(0)
	v_mul_f32_e32 v1, v150, v150
	v_mul_f32_e32 v0, v1, v0
	v_fmamk_f32 v0, v0, 0x3c800000, v194
	v_rsq_f32_e32 v0, v0
	s_nop 0
	v_mul_f32_e32 v0, v150, v0
	v_pk_mul_f32 v[186:187], v[16:17], v[0:1] op_sel_hi:[1,0]
	v_pk_mul_f32 v[2:3], v[18:19], v[0:1] op_sel_hi:[1,0]
	v_pk_mul_f32 v[4:5], v[20:21], v[0:1] op_sel_hi:[1,0]
	v_pk_mul_f32 v[6:7], v[22:23], v[0:1] op_sel_hi:[1,0]
	v_pk_mul_f32 v[8:9], v[24:25], v[0:1] op_sel_hi:[1,0]
	v_pk_mul_f32 v[10:11], v[26:27], v[0:1] op_sel_hi:[1,0]
	v_pk_mul_f32 v[12:13], v[28:29], v[0:1] op_sel_hi:[1,0]
	v_pk_mul_f32 v[0:1], v[30:31], v[0:1] op_sel_hi:[1,0]
	v_pk_mul_f32 v[12:13], v[174:175], v[12:13]
	v_pk_mul_f32 v[14:15], v[176:177], v[0:1]
	v_pk_mul_f32 v[10:11], v[172:173], v[10:11]
	v_pk_mul_f32 v[8:9], v[170:171], v[8:9]
	v_pk_mul_f32 v[6:7], v[168:169], v[6:7]
	v_pk_mul_f32 v[4:5], v[166:167], v[4:5]
	v_pk_mul_f32 v[2:3], v[164:165], v[2:3]
	v_pk_mul_f32 v[0:1], v[162:163], v[186:187]
	s_cbranch_execnz .LBB0_514

.LBB0_526:
	s_andn2_b64 vcc, exec, s[4:5]
	s_cbranch_vccnz .LBB0_533
	s_and_b64 vcc, exec, s[10:11]
	s_cbranch_vccnz .LBB0_633
	v_mul_f32_e32 v4, v129, v129
	v_fmac_f32_e32 v4, v128, v128
	v_fmac_f32_e32 v4, v130, v130
	v_fmac_f32_e32 v4, v131, v131
	v_fmac_f32_e32 v4, v132, v132
	v_fmac_f32_e32 v4, v133, v133
	v_fmac_f32_e32 v4, v134, v134
	v_fmac_f32_e32 v4, v135, v135
	v_pk_mul_f32 v[2:3], v[136:137], v[136:137]
	v_pk_mul_f32 v[0:1], v[138:139], v[138:139]
	v_add_f32_e32 v2, v2, v4
	v_add_f32_e32 v2, v3, v2
	v_add_f32_e32 v0, v0, v2
	v_add_f32_e32 v4, v1, v0
	v_pk_mul_f32 v[2:3], v[140:141], v[140:141]
	v_pk_mul_f32 v[0:1], v[142:143], v[142:143]
	v_add_f32_e32 v2, v2, v4
	v_add_f32_e32 v2, v3, v2
	v_add_f32_e32 v0, v0, v2
	v_add_f32_e32 v0, v1, v0
	ds_bpermute_b32 v1, v252, v0
	s_waitcnt lgkmcnt(0)
	v_add_f32_e32 v0, v0, v1
	ds_bpermute_b32 v1, v253, v0
	s_waitcnt lgkmcnt(0)
	v_add_f32_e32 v0, v0, v1
	v_mul_f32_e32 v1, v16, v16
	v_mul_f32_e32 v0, v1, v0
	v_fmamk_f32 v0, v0, 0x3c800000, v194
	v_rsq_f32_e32 v0, v0
	s_nop 0
	v_mul_f32_e32 v0, v16, v0
	v_pk_mul_f32 v[18:19], v[128:129], v[0:1] op_sel_hi:[1,0]
	v_pk_mul_f32 v[2:3], v[130:131], v[0:1] op_sel_hi:[1,0]
	v_pk_mul_f32 v[4:5], v[132:133], v[0:1] op_sel_hi:[1,0]
	v_pk_mul_f32 v[6:7], v[134:135], v[0:1] op_sel_hi:[1,0]
	v_pk_mul_f32 v[8:9], v[136:137], v[0:1] op_sel_hi:[1,0]
	v_pk_mul_f32 v[10:11], v[138:139], v[0:1] op_sel_hi:[1,0]
	v_pk_mul_f32 v[12:13], v[140:141], v[0:1] op_sel_hi:[1,0]
	v_pk_mul_f32 v[0:1], v[142:143], v[0:1] op_sel_hi:[1,0]
	v_pk_mul_f32 v[12:13], v[174:175], v[12:13]
	v_pk_mul_f32 v[14:15], v[176:177], v[0:1]
	v_pk_mul_f32 v[10:11], v[172:173], v[10:11]
	v_pk_mul_f32 v[8:9], v[170:171], v[8:9]
	v_pk_mul_f32 v[6:7], v[168:169], v[6:7]
	v_pk_mul_f32 v[4:5], v[166:167], v[4:5]
	v_pk_mul_f32 v[2:3], v[164:165], v[2:3]
	v_pk_mul_f32 v[0:1], v[162:163], v[18:19]
	s_cbranch_execnz .LBB0_530

.LBB0_542:
	s_andn2_b64 vcc, exec, s[4:5]
	s_cbranch_vccnz .LBB0_549
	s_and_b64 vcc, exec, s[10:11]
	s_cbranch_vccnz .LBB0_634
	v_mul_f32_e32 v4, v113, v113
	v_fmac_f32_e32 v4, v112, v112
	v_fmac_f32_e32 v4, v114, v114
	v_fmac_f32_e32 v4, v115, v115
	v_fmac_f32_e32 v4, v116, v116
	v_fmac_f32_e32 v4, v117, v117
	v_fmac_f32_e32 v4, v118, v118
	v_fmac_f32_e32 v4, v119, v119
	v_pk_mul_f32 v[2:3], v[120:121], v[120:121]
	v_pk_mul_f32 v[0:1], v[122:123], v[122:123]
	v_add_f32_e32 v2, v2, v4
	v_add_f32_e32 v2, v3, v2
	v_add_f32_e32 v0, v0, v2
	v_add_f32_e32 v4, v1, v0
	v_pk_mul_f32 v[2:3], v[124:125], v[124:125]
	v_pk_mul_f32 v[0:1], v[126:127], v[126:127]
	v_add_f32_e32 v2, v2, v4
	v_add_f32_e32 v2, v3, v2
	v_add_f32_e32 v0, v0, v2
	v_add_f32_e32 v0, v1, v0
	ds_bpermute_b32 v1, v252, v0
	s_waitcnt lgkmcnt(0)
	v_add_f32_e32 v0, v0, v1
	ds_bpermute_b32 v1, v253, v0
	s_waitcnt lgkmcnt(0)
	v_add_f32_e32 v0, v0, v1
	v_mul_f32_e32 v1, v16, v16
	v_mul_f32_e32 v0, v1, v0
	v_fmamk_f32 v0, v0, 0x3c800000, v194
	v_rsq_f32_e32 v0, v0
	s_nop 0
	v_mul_f32_e32 v0, v16, v0
	v_pk_mul_f32 v[18:19], v[112:113], v[0:1] op_sel_hi:[1,0]
	v_pk_mul_f32 v[2:3], v[114:115], v[0:1] op_sel_hi:[1,0]
	v_pk_mul_f32 v[4:5], v[116:117], v[0:1] op_sel_hi:[1,0]
	v_pk_mul_f32 v[6:7], v[118:119], v[0:1] op_sel_hi:[1,0]
	v_pk_mul_f32 v[8:9], v[120:121], v[0:1] op_sel_hi:[1,0]
	v_pk_mul_f32 v[10:11], v[122:123], v[0:1] op_sel_hi:[1,0]
	v_pk_mul_f32 v[12:13], v[124:125], v[0:1] op_sel_hi:[1,0]
	v_pk_mul_f32 v[0:1], v[126:127], v[0:1] op_sel_hi:[1,0]
	v_pk_mul_f32 v[12:13], v[174:175], v[12:13]
	v_pk_mul_f32 v[14:15], v[176:177], v[0:1]
	v_pk_mul_f32 v[10:11], v[172:173], v[10:11]
	v_pk_mul_f32 v[8:9], v[170:171], v[8:9]
	v_pk_mul_f32 v[6:7], v[168:169], v[6:7]
	v_pk_mul_f32 v[4:5], v[166:167], v[4:5]
	v_pk_mul_f32 v[2:3], v[164:165], v[2:3]
	v_pk_mul_f32 v[0:1], v[162:163], v[18:19]
	s_cbranch_execnz .LBB0_546

.LBB0_558:
	s_andn2_b64 vcc, exec, s[4:5]
	s_cbranch_vccnz .LBB0_565
	s_and_b64 vcc, exec, s[10:11]
	s_cbranch_vccnz .LBB0_635
	v_mul_f32_e32 v4, v97, v97
	v_fmac_f32_e32 v4, v96, v96
	v_fmac_f32_e32 v4, v98, v98
	v_fmac_f32_e32 v4, v99, v99
	v_fmac_f32_e32 v4, v100, v100
	v_fmac_f32_e32 v4, v101, v101
	v_fmac_f32_e32 v4, v102, v102
	v_fmac_f32_e32 v4, v103, v103
	v_pk_mul_f32 v[2:3], v[104:105], v[104:105]
	v_pk_mul_f32 v[0:1], v[106:107], v[106:107]
	v_add_f32_e32 v2, v2, v4
	v_add_f32_e32 v2, v3, v2
	v_add_f32_e32 v0, v0, v2
	v_add_f32_e32 v4, v1, v0
	v_pk_mul_f32 v[2:3], v[108:109], v[108:109]
	v_pk_mul_f32 v[0:1], v[110:111], v[110:111]
	v_add_f32_e32 v2, v2, v4
	v_add_f32_e32 v2, v3, v2
	v_add_f32_e32 v0, v0, v2
	v_add_f32_e32 v0, v1, v0
	ds_bpermute_b32 v1, v252, v0
	s_waitcnt lgkmcnt(0)
	v_add_f32_e32 v0, v0, v1
	ds_bpermute_b32 v1, v253, v0
	s_waitcnt lgkmcnt(0)
	v_add_f32_e32 v0, v0, v1
	v_mul_f32_e32 v1, v16, v16
	v_mul_f32_e32 v0, v1, v0
	v_fmamk_f32 v0, v0, 0x3c800000, v194
	v_rsq_f32_e32 v0, v0
	s_nop 0
	v_mul_f32_e32 v0, v16, v0
	v_pk_mul_f32 v[18:19], v[96:97], v[0:1] op_sel_hi:[1,0]
	v_pk_mul_f32 v[2:3], v[98:99], v[0:1] op_sel_hi:[1,0]
	v_pk_mul_f32 v[4:5], v[100:101], v[0:1] op_sel_hi:[1,0]
	v_pk_mul_f32 v[6:7], v[102:103], v[0:1] op_sel_hi:[1,0]
	v_pk_mul_f32 v[8:9], v[104:105], v[0:1] op_sel_hi:[1,0]
	v_pk_mul_f32 v[10:11], v[106:107], v[0:1] op_sel_hi:[1,0]
	v_pk_mul_f32 v[12:13], v[108:109], v[0:1] op_sel_hi:[1,0]
	v_pk_mul_f32 v[0:1], v[110:111], v[0:1] op_sel_hi:[1,0]
	v_pk_mul_f32 v[12:13], v[174:175], v[12:13]
	v_pk_mul_f32 v[14:15], v[176:177], v[0:1]
	v_pk_mul_f32 v[10:11], v[172:173], v[10:11]
	v_pk_mul_f32 v[8:9], v[170:171], v[8:9]
	v_pk_mul_f32 v[6:7], v[168:169], v[6:7]
	v_pk_mul_f32 v[4:5], v[166:167], v[4:5]
	v_pk_mul_f32 v[2:3], v[164:165], v[2:3]
	v_pk_mul_f32 v[0:1], v[162:163], v[18:19]
	s_cbranch_execnz .LBB0_562

.LBB0_574:
	s_ashr_i32 s72, s76, 11
	s_mul_i32 s65, s65, s72
	s_add_i32 s72, s65, s63
	s_ashr_i32 s73, s72, 31
	s_lshl_b64 s[72:73], s[72:73], 18
	s_andn2_b64 vcc, exec, s[4:5]
	v_lshl_add_u64 v[96:97], v[180:181], 0, s[72:73]
	s_cbranch_vccnz .LBB0_581
	s_and_b64 vcc, exec, s[10:11]
	s_cbranch_vccnz .LBB0_636
	v_mul_f32_e32 v4, v81, v81
	v_fmac_f32_e32 v4, v80, v80
	v_fmac_f32_e32 v4, v82, v82
	v_fmac_f32_e32 v4, v83, v83
	v_fmac_f32_e32 v4, v84, v84
	v_fmac_f32_e32 v4, v85, v85
	v_fmac_f32_e32 v4, v86, v86
	v_fmac_f32_e32 v4, v87, v87
	v_pk_mul_f32 v[2:3], v[88:89], v[88:89]
	v_pk_mul_f32 v[0:1], v[90:91], v[90:91]
	v_add_f32_e32 v2, v2, v4
	v_add_f32_e32 v2, v3, v2
	v_add_f32_e32 v0, v0, v2
	v_add_f32_e32 v4, v1, v0
	v_pk_mul_f32 v[2:3], v[92:93], v[92:93]
	v_pk_mul_f32 v[0:1], v[94:95], v[94:95]
	v_add_f32_e32 v2, v2, v4
	v_add_f32_e32 v2, v3, v2
	v_add_f32_e32 v0, v0, v2
	v_add_f32_e32 v0, v1, v0
	ds_bpermute_b32 v1, v252, v0
	s_waitcnt lgkmcnt(0)
	v_add_f32_e32 v0, v0, v1
	ds_bpermute_b32 v1, v253, v0
	s_waitcnt lgkmcnt(0)
	v_add_f32_e32 v0, v0, v1
	v_mul_f32_e32 v1, v16, v16
	v_mul_f32_e32 v0, v1, v0
	v_fmamk_f32 v0, v0, 0x3c800000, v194
	v_rsq_f32_e32 v0, v0
	s_nop 0
	v_mul_f32_e32 v0, v16, v0
	v_pk_mul_f32 v[18:19], v[80:81], v[0:1] op_sel_hi:[1,0]
	v_pk_mul_f32 v[2:3], v[82:83], v[0:1] op_sel_hi:[1,0]
	v_pk_mul_f32 v[4:5], v[84:85], v[0:1] op_sel_hi:[1,0]
	v_pk_mul_f32 v[6:7], v[86:87], v[0:1] op_sel_hi:[1,0]
	v_pk_mul_f32 v[8:9], v[88:89], v[0:1] op_sel_hi:[1,0]
	v_pk_mul_f32 v[10:11], v[90:91], v[0:1] op_sel_hi:[1,0]
	v_pk_mul_f32 v[12:13], v[92:93], v[0:1] op_sel_hi:[1,0]
	v_pk_mul_f32 v[0:1], v[94:95], v[0:1] op_sel_hi:[1,0]
	v_pk_mul_f32 v[12:13], v[174:175], v[12:13]
	v_pk_mul_f32 v[14:15], v[176:177], v[0:1]
	v_pk_mul_f32 v[10:11], v[172:173], v[10:11]
	v_pk_mul_f32 v[8:9], v[170:171], v[8:9]
	v_pk_mul_f32 v[6:7], v[168:169], v[6:7]
	v_pk_mul_f32 v[4:5], v[166:167], v[4:5]
	v_pk_mul_f32 v[2:3], v[164:165], v[2:3]
	v_pk_mul_f32 v[0:1], v[162:163], v[18:19]
	s_cbranch_execnz .LBB0_578

.LBB0_590:
	s_andn2_b64 vcc, exec, s[4:5]
	s_cbranch_vccnz .LBB0_597
	s_and_b64 vcc, exec, s[10:11]
	s_cbranch_vccnz .LBB0_637
	v_mul_f32_e32 v4, v65, v65
	v_fmac_f32_e32 v4, v64, v64
	v_fmac_f32_e32 v4, v66, v66
	v_fmac_f32_e32 v4, v67, v67
	v_fmac_f32_e32 v4, v68, v68
	v_fmac_f32_e32 v4, v69, v69
	v_fmac_f32_e32 v4, v70, v70
	v_fmac_f32_e32 v4, v71, v71
	v_pk_mul_f32 v[2:3], v[72:73], v[72:73]
	v_pk_mul_f32 v[0:1], v[74:75], v[74:75]
	v_add_f32_e32 v2, v2, v4
	v_add_f32_e32 v2, v3, v2
	v_add_f32_e32 v0, v0, v2
	v_add_f32_e32 v4, v1, v0
	v_pk_mul_f32 v[2:3], v[76:77], v[76:77]
	v_pk_mul_f32 v[0:1], v[78:79], v[78:79]
	v_add_f32_e32 v2, v2, v4
	v_add_f32_e32 v2, v3, v2
	v_add_f32_e32 v0, v0, v2
	v_add_f32_e32 v0, v1, v0
	ds_bpermute_b32 v1, v252, v0
	s_waitcnt lgkmcnt(0)
	v_add_f32_e32 v0, v0, v1
	ds_bpermute_b32 v1, v253, v0
	s_waitcnt lgkmcnt(0)
	v_add_f32_e32 v0, v0, v1
	v_mul_f32_e32 v1, v16, v16
	v_mul_f32_e32 v0, v1, v0
	v_fmamk_f32 v0, v0, 0x3c800000, v194
	v_rsq_f32_e32 v0, v0
	s_nop 0
	v_mul_f32_e32 v0, v16, v0
	v_pk_mul_f32 v[18:19], v[64:65], v[0:1] op_sel_hi:[1,0]
	v_pk_mul_f32 v[2:3], v[66:67], v[0:1] op_sel_hi:[1,0]
	v_pk_mul_f32 v[4:5], v[68:69], v[0:1] op_sel_hi:[1,0]
	v_pk_mul_f32 v[6:7], v[70:71], v[0:1] op_sel_hi:[1,0]
	v_pk_mul_f32 v[8:9], v[72:73], v[0:1] op_sel_hi:[1,0]
	v_pk_mul_f32 v[10:11], v[74:75], v[0:1] op_sel_hi:[1,0]
	v_pk_mul_f32 v[12:13], v[76:77], v[0:1] op_sel_hi:[1,0]
	v_pk_mul_f32 v[0:1], v[78:79], v[0:1] op_sel_hi:[1,0]
	v_pk_mul_f32 v[12:13], v[174:175], v[12:13]
	v_pk_mul_f32 v[14:15], v[176:177], v[0:1]
	v_pk_mul_f32 v[10:11], v[172:173], v[10:11]
	v_pk_mul_f32 v[8:9], v[170:171], v[8:9]
	v_pk_mul_f32 v[6:7], v[168:169], v[6:7]
	v_pk_mul_f32 v[4:5], v[166:167], v[4:5]
	v_pk_mul_f32 v[2:3], v[164:165], v[2:3]
	v_pk_mul_f32 v[0:1], v[162:163], v[18:19]
	s_cbranch_execnz .LBB0_594

.LBB0_606:
	s_andn2_b64 vcc, exec, s[4:5]
	s_cbranch_vccnz .LBB0_613
	s_and_b64 vcc, exec, s[10:11]
	s_cbranch_vccnz .LBB0_638
	v_mul_f32_e32 v4, v49, v49
	v_fmac_f32_e32 v4, v48, v48
	v_fmac_f32_e32 v4, v50, v50
	v_fmac_f32_e32 v4, v51, v51
	v_fmac_f32_e32 v4, v52, v52
	v_fmac_f32_e32 v4, v53, v53
	v_fmac_f32_e32 v4, v54, v54
	v_fmac_f32_e32 v4, v55, v55
	v_pk_mul_f32 v[2:3], v[56:57], v[56:57]
	v_pk_mul_f32 v[0:1], v[58:59], v[58:59]
	v_add_f32_e32 v2, v2, v4
	v_add_f32_e32 v2, v3, v2
	v_add_f32_e32 v0, v0, v2
	v_add_f32_e32 v4, v1, v0
	v_pk_mul_f32 v[2:3], v[60:61], v[60:61]
	v_pk_mul_f32 v[0:1], v[62:63], v[62:63]
	v_add_f32_e32 v2, v2, v4
	v_add_f32_e32 v2, v3, v2
	v_add_f32_e32 v0, v0, v2
	v_add_f32_e32 v0, v1, v0
	ds_bpermute_b32 v1, v252, v0
	s_waitcnt lgkmcnt(0)
	v_add_f32_e32 v0, v0, v1
	ds_bpermute_b32 v1, v253, v0
	s_waitcnt lgkmcnt(0)
	v_add_f32_e32 v0, v0, v1
	v_mul_f32_e32 v1, v16, v16
	v_mul_f32_e32 v0, v1, v0
	v_fmamk_f32 v0, v0, 0x3c800000, v194
	v_rsq_f32_e32 v0, v0
	s_nop 0
	v_mul_f32_e32 v0, v16, v0
	v_pk_mul_f32 v[18:19], v[48:49], v[0:1] op_sel_hi:[1,0]
	v_pk_mul_f32 v[2:3], v[50:51], v[0:1] op_sel_hi:[1,0]
	v_pk_mul_f32 v[4:5], v[52:53], v[0:1] op_sel_hi:[1,0]
	v_pk_mul_f32 v[6:7], v[54:55], v[0:1] op_sel_hi:[1,0]
	v_pk_mul_f32 v[8:9], v[56:57], v[0:1] op_sel_hi:[1,0]
	v_pk_mul_f32 v[10:11], v[58:59], v[0:1] op_sel_hi:[1,0]
	v_pk_mul_f32 v[12:13], v[60:61], v[0:1] op_sel_hi:[1,0]
	v_pk_mul_f32 v[0:1], v[62:63], v[0:1] op_sel_hi:[1,0]
	v_pk_mul_f32 v[12:13], v[174:175], v[12:13]
	v_pk_mul_f32 v[14:15], v[176:177], v[0:1]
	v_pk_mul_f32 v[10:11], v[172:173], v[10:11]
	v_pk_mul_f32 v[8:9], v[170:171], v[8:9]
	v_pk_mul_f32 v[6:7], v[168:169], v[6:7]
	v_pk_mul_f32 v[4:5], v[166:167], v[4:5]
	v_pk_mul_f32 v[2:3], v[164:165], v[2:3]
	v_pk_mul_f32 v[0:1], v[162:163], v[18:19]
	s_cbranch_execnz .LBB0_610

.LBB0_622:
	s_andn2_b64 vcc, exec, s[4:5]
	s_cbranch_vccnz .LBB0_629
	s_and_b64 vcc, exec, s[10:11]
	s_cbranch_vccnz .LBB0_639
	v_mul_f32_e32 v4, v37, v37
	v_fmac_f32_e32 v4, v36, v36
	v_fmac_f32_e32 v4, v38, v38
	v_fmac_f32_e32 v4, v39, v39
	v_fmac_f32_e32 v4, v40, v40
	v_fmac_f32_e32 v4, v41, v41
	v_fmac_f32_e32 v4, v42, v42
	v_fmac_f32_e32 v4, v43, v43
	v_pk_mul_f32 v[2:3], v[44:45], v[44:45]
	v_pk_mul_f32 v[0:1], v[46:47], v[46:47]
	v_add_f32_e32 v2, v2, v4
	v_add_f32_e32 v2, v3, v2
	v_add_f32_e32 v0, v0, v2
	v_add_f32_e32 v4, v1, v0
	v_pk_mul_f32 v[2:3], v[32:33], v[32:33]
	v_pk_mul_f32 v[0:1], v[34:35], v[34:35]
	v_add_f32_e32 v2, v2, v4
	v_add_f32_e32 v2, v3, v2
	v_add_f32_e32 v0, v0, v2
	v_add_f32_e32 v0, v1, v0
	ds_bpermute_b32 v1, v252, v0
	s_waitcnt lgkmcnt(0)
	v_add_f32_e32 v0, v0, v1
	ds_bpermute_b32 v1, v253, v0
	s_waitcnt lgkmcnt(0)
	v_add_f32_e32 v0, v0, v1
	v_mul_f32_e32 v1, v16, v16
	v_mul_f32_e32 v0, v1, v0
	v_fmamk_f32 v0, v0, 0x3c800000, v194
	v_rsq_f32_e32 v0, v0
	s_nop 0
	v_mul_f32_e32 v0, v16, v0
	v_pk_mul_f32 v[18:19], v[36:37], v[0:1] op_sel_hi:[1,0]
	v_pk_mul_f32 v[2:3], v[38:39], v[0:1] op_sel_hi:[1,0]
	v_pk_mul_f32 v[4:5], v[40:41], v[0:1] op_sel_hi:[1,0]
	v_pk_mul_f32 v[6:7], v[42:43], v[0:1] op_sel_hi:[1,0]
	v_pk_mul_f32 v[8:9], v[44:45], v[0:1] op_sel_hi:[1,0]
	v_pk_mul_f32 v[10:11], v[46:47], v[0:1] op_sel_hi:[1,0]
	v_pk_mul_f32 v[12:13], v[32:33], v[0:1] op_sel_hi:[1,0]
	v_pk_mul_f32 v[0:1], v[34:35], v[0:1] op_sel_hi:[1,0]
	v_pk_mul_f32 v[12:13], v[174:175], v[12:13]
	v_pk_mul_f32 v[14:15], v[176:177], v[0:1]
	v_pk_mul_f32 v[10:11], v[172:173], v[10:11]
	v_pk_mul_f32 v[8:9], v[170:171], v[8:9]
	v_pk_mul_f32 v[6:7], v[168:169], v[6:7]
	v_pk_mul_f32 v[4:5], v[166:167], v[4:5]
	v_pk_mul_f32 v[2:3], v[164:165], v[2:3]
	v_pk_mul_f32 v[0:1], v[162:163], v[18:19]
	s_cbranch_execnz .LBB0_626

.LBB0_1467:
	v_lshl_add_u32 v138, s28, 8, v140
	v_ashrrev_i32_e32 v139, 31, v138
	v_lshlrev_b64 v[176:177], 6, v[138:139]
	v_lshl_add_u64 v[176:177], s[8:9], 0, v[176:177]
	v_and_b32_e32 v178, 48, v188
	v_mov_b32_e32 v179, 0
	s_mov_b64 s[98:99], 0x2000
	v_lshl_add_u64 v[176:177], v[176:177], 0, v[178:179]
	v_lshl_add_u64 v[178:179], v[176:177], 0, s[98:99]
	global_load_dwordx4 v[180:183], v[176:177], off
	global_load_dwordx4 v[184:187], v[176:177], off offset:1024
	global_load_dwordx4 v[192:195], v[176:177], off offset:2048
	global_load_dwordx4 v[196:199], v[176:177], off offset:3072
	global_load_dwordx4 v[200:203], v[178:179], off
	global_load_dwordx4 v[204:207], v[178:179], off offset:1024
	global_load_dwordx4 v[208:211], v[178:179], off offset:2048
	global_load_dwordx4 v[212:215], v[178:179], off offset:3072
	v_and_b32_e32 v174, 15, v188
	v_lshlrev_b32_e32 v216, 2, v174
	v_add_u32_e32 v217, 64, v216
	v_add_u32_e32 v218, 128, v216
	v_add_u32_e32 v219, 192, v216
	v_lshlrev_b64 v[148:149], 6, v[138:139]
	v_lshl_add_u64 v[160:161], s[8:9], 0, v[148:149]
	v_lshl_or_b32 v164, s26, 7, v142
	v_ashrrev_i32_e32 v165, 31, v164
	v_pk_mul_f32 v[166:167], v[122:123], v[114:115]
	v_lshlrev_b64 v[122:123], 1, v[164:165]
	v_pk_mul_f32 v[126:127], v[126:127], v[118:119]
	v_pk_mul_f32 v[124:125], v[124:125], v[116:117]
	v_pk_mul_f32 v[168:169], v[120:121], v[112:113]
	v_mov_b64_e32 v[120:121], s[10:11]
	v_or_b32_e32 v172, 16, v138
	v_mad_i64_i32 v[170:171], s[4:5], v138, s55, v[120:121]
	v_ashrrev_i32_e32 v173, 31, v172
	v_pk_mul_f32 v[110:111], v[110:111], v[102:103]
	v_pk_mul_f32 v[108:109], v[108:109], v[100:101]
	v_pk_mul_f32 v[106:107], v[106:107], v[98:99]
	v_pk_mul_f32 v[104:105], v[104:105], v[96:97]
	v_pk_mul_f32 v[94:95], v[94:95], v[86:87]
	v_pk_mul_f32 v[92:93], v[92:93], v[84:85]
	v_pk_mul_f32 v[90:91], v[90:91], v[82:83]
	v_pk_mul_f32 v[88:89], v[88:89], v[80:81]
	v_pk_mul_f32 v[78:79], v[78:79], v[70:71]
	v_pk_mul_f32 v[76:77], v[76:77], v[68:69]
	v_pk_mul_f32 v[74:75], v[74:75], v[66:67]
	v_pk_mul_f32 v[72:73], v[72:73], v[64:65]
	v_pk_mul_f32 v[62:63], v[62:63], v[54:55]
	v_pk_mul_f32 v[60:61], v[60:61], v[52:53]
	v_pk_mul_f32 v[58:59], v[58:59], v[50:51]
	v_pk_mul_f32 v[56:57], v[56:57], v[48:49]
	v_pk_mul_f32 v[46:47], v[46:47], v[38:39]
	v_pk_mul_f32 v[44:45], v[44:45], v[36:37]
	v_pk_mul_f32 v[42:43], v[42:43], v[34:35]
	v_pk_mul_f32 v[40:41], v[40:41], v[32:33]
	v_pk_mul_f32 v[30:31], v[30:31], v[22:23]
	v_pk_mul_f32 v[28:29], v[28:29], v[20:21]
	v_pk_mul_f32 v[26:27], v[26:27], v[18:19]
	v_pk_mul_f32 v[24:25], v[24:25], v[16:17]
	v_pk_mul_f32 v[14:15], v[14:15], v[6:7]
	v_pk_mul_f32 v[12:13], v[12:13], v[4:5]
	v_pk_mul_f32 v[10:11], v[10:11], v[2:3]
	v_pk_mul_f32 v[8:9], v[8:9], v[0:1]
	s_cmp_eq_u32 s45, s49
	s_waitcnt vmcnt(0)
	v_add_f32_e32 v180, v180, v181
	v_add_f32_e32 v182, v182, v183
	v_add_f32_e32 v184, v184, v185
	v_add_f32_e32 v186, v186, v187
	v_add_f32_e32 v192, v192, v193
	v_add_f32_e32 v194, v194, v195
	v_add_f32_e32 v196, v196, v197
	v_add_f32_e32 v198, v198, v199
	v_add_f32_e32 v200, v200, v201
	v_add_f32_e32 v202, v202, v203
	v_add_f32_e32 v204, v204, v205
	v_add_f32_e32 v206, v206, v207
	v_add_f32_e32 v208, v208, v209
	v_add_f32_e32 v210, v210, v211
	v_add_f32_e32 v212, v212, v213
	v_add_f32_e32 v214, v214, v215
	v_add_f32_e32 v180, v180, v182
	v_add_f32_e32 v184, v184, v186
	v_add_f32_e32 v192, v192, v194
	v_add_f32_e32 v196, v196, v198
	v_add_f32_e32 v200, v200, v202
	v_add_f32_e32 v204, v204, v206
	v_add_f32_e32 v208, v208, v210
	v_add_f32_e32 v212, v212, v214
	ds_bpermute_b32 v181, v216, v180
	ds_bpermute_b32 v185, v216, v184
	ds_bpermute_b32 v193, v216, v192
	ds_bpermute_b32 v197, v216, v196
	ds_bpermute_b32 v201, v216, v200
	ds_bpermute_b32 v205, v216, v204
	ds_bpermute_b32 v209, v216, v208
	ds_bpermute_b32 v213, v216, v212
	s_waitcnt lgkmcnt(0)
	ds_bpermute_b32 v182, v217, v180
	ds_bpermute_b32 v186, v217, v184
	ds_bpermute_b32 v194, v217, v192
	ds_bpermute_b32 v198, v217, v196
	ds_bpermute_b32 v202, v217, v200
	ds_bpermute_b32 v206, v217, v204
	ds_bpermute_b32 v210, v217, v208
	ds_bpermute_b32 v214, v217, v212
	s_waitcnt lgkmcnt(0)
	v_add_f32_e32 v181, v181, v182
	v_add_f32_e32 v185, v185, v186
	v_add_f32_e32 v193, v193, v194
	v_add_f32_e32 v197, v197, v198
	v_add_f32_e32 v201, v201, v202
	v_add_f32_e32 v205, v205, v206
	v_add_f32_e32 v209, v209, v210
	v_add_f32_e32 v213, v213, v214
	ds_bpermute_b32 v182, v218, v180
	ds_bpermute_b32 v186, v218, v184
	ds_bpermute_b32 v194, v218, v192
	ds_bpermute_b32 v198, v218, v196
	ds_bpermute_b32 v202, v218, v200
	ds_bpermute_b32 v206, v218, v204
	ds_bpermute_b32 v210, v218, v208
	ds_bpermute_b32 v214, v218, v212
	s_waitcnt lgkmcnt(0)
	v_add_f32_e32 v181, v181, v182
	v_add_f32_e32 v185, v185, v186
	v_add_f32_e32 v193, v193, v194
	v_add_f32_e32 v197, v197, v198
	v_add_f32_e32 v201, v201, v202
	v_add_f32_e32 v205, v205, v206
	v_add_f32_e32 v209, v209, v210
	v_add_f32_e32 v213, v213, v214
	ds_bpermute_b32 v182, v219, v180
	ds_bpermute_b32 v186, v219, v184
	ds_bpermute_b32 v194, v219, v192
	ds_bpermute_b32 v198, v219, v196
	ds_bpermute_b32 v202, v219, v200
	ds_bpermute_b32 v206, v219, v204
	ds_bpermute_b32 v210, v219, v208
	ds_bpermute_b32 v214, v219, v212
	s_waitcnt lgkmcnt(0)
	v_add_f32_e32 v181, v181, v182
	v_add_f32_e32 v185, v185, v186
	v_add_f32_e32 v193, v193, v194
	v_add_f32_e32 v197, v197, v198
	v_add_f32_e32 v201, v201, v202
	v_add_f32_e32 v205, v205, v206
	v_add_f32_e32 v209, v209, v210
	v_add_f32_e32 v213, v213, v214
	v_lshlrev_b64 v[150:151], 6, v[172:173]
	v_lshl_add_u64 v[150:151], s[8:9], 0, v[150:151]
	v_fmamk_f32 v139, v181, 0x3a800000, v146
	v_lshl_add_u64 v[148:149], v[170:171], 0, v[122:123]
	v_mad_i64_i32 v[154:155], s[4:5], v172, s55, v[120:121]
	v_rsq_f32_e32 v139, v139
	s_nop 0
	v_mul_f32_e32 v147, 0xbfb8aa3b, v139
	v_mul_f32_e32 v139, v139, v139
	v_mul_f32_e32 v116, v116, v147
	v_mul_f32_e32 v117, v117, v147
	v_mul_f32_e32 v118, v118, v147
	v_mul_f32_e32 v119, v119, v147
	v_mul_f32_e32 v112, v112, v147
	v_mul_f32_e32 v113, v113, v147
	v_mul_f32_e32 v114, v114, v147
	v_mul_f32_e32 v115, v115, v147
	v_rcp_f32_e32 v139, v139
	v_exp_f32_e32 v116, v116
	v_exp_f32_e32 v117, v117
	v_exp_f32_e32 v118, v118
	v_exp_f32_e32 v119, v119
	v_exp_f32_e32 v112, v112
	v_exp_f32_e32 v113, v113
	v_exp_f32_e32 v114, v114
	v_exp_f32_e32 v115, v115
	v_fma_f32 v116, v116, v139, v139
	v_fma_f32 v117, v117, v139, v139
	v_fma_f32 v118, v118, v139, v139
	v_fma_f32 v119, v119, v139, v139
	v_fma_f32 v147, v112, v139, v139
	v_fma_f32 v152, v113, v139, v139
	v_fma_f32 v153, v114, v139, v139
	v_fmac_f32_e32 v139, v115, v139
	v_rcp_f32_e32 v112, v116
	v_rcp_f32_e32 v113, v117
	v_rcp_f32_e32 v114, v118
	v_rcp_f32_e32 v115, v119
	v_rcp_f32_e32 v116, v147
	v_rcp_f32_e32 v117, v152
	v_rcp_f32_e32 v118, v153
	v_rcp_f32_e32 v119, v139
	v_pk_mul_f32 v[112:113], v[124:125], v[112:113]
	v_pk_mul_f32 v[114:115], v[126:127], v[114:115]
	v_pk_mul_f32 v[116:117], v[168:169], v[116:117]
	v_pk_mul_f32 v[118:119], v[166:167], v[118:119]
	v_cvt_pk_bf16_f32 v112, v112, v113
	v_cvt_pk_bf16_f32 v113, v114, v115
	v_cvt_pk_bf16_f32 v114, v116, v117
	v_cvt_pk_bf16_f32 v115, v118, v119
	global_store_dwordx4 v[148:149], v[112:115], off
	v_or_b32_e32 v152, 32, v138
	v_ashrrev_i32_e32 v153, 31, v152
	v_fmamk_f32 v112, v185, 0x3a800000, v146
	v_rsq_f32_e32 v116, v112
	v_lshl_add_u64 v[112:113], v[154:155], 0, v[122:123]
	v_mul_f32_e32 v117, 0xbfb8aa3b, v116
	v_mul_f32_e32 v116, v116, v116
	v_mul_f32_e32 v100, v100, v117
	v_mul_f32_e32 v101, v101, v117
	v_mul_f32_e32 v102, v102, v117
	v_mul_f32_e32 v103, v103, v117
	v_mul_f32_e32 v96, v96, v117
	v_mul_f32_e32 v97, v97, v117
	v_mul_f32_e32 v98, v98, v117
	v_mul_f32_e32 v99, v99, v117
	v_rcp_f32_e32 v116, v116
	v_exp_f32_e32 v100, v100
	v_exp_f32_e32 v101, v101
	v_exp_f32_e32 v102, v102
	v_exp_f32_e32 v103, v103
	v_exp_f32_e32 v96, v96
	v_exp_f32_e32 v97, v97
	v_exp_f32_e32 v98, v98
	v_exp_f32_e32 v99, v99
	v_fma_f32 v100, v100, v116, v116
	v_fma_f32 v101, v101, v116, v116
	v_fma_f32 v102, v102, v116, v116
	v_fma_f32 v103, v103, v116, v116
	v_fma_f32 v117, v96, v116, v116
	v_fma_f32 v118, v97, v116, v116
	v_fma_f32 v119, v98, v116, v116
	v_fmac_f32_e32 v116, v99, v116
	v_rcp_f32_e32 v96, v100
	v_rcp_f32_e32 v97, v101
	v_rcp_f32_e32 v98, v102
	v_rcp_f32_e32 v99, v103
	v_rcp_f32_e32 v100, v117
	v_rcp_f32_e32 v101, v118
	v_rcp_f32_e32 v102, v119
	v_rcp_f32_e32 v103, v116
	v_pk_mul_f32 v[96:97], v[108:109], v[96:97]
	v_pk_mul_f32 v[98:99], v[110:111], v[98:99]
	v_pk_mul_f32 v[100:101], v[104:105], v[100:101]
	v_pk_mul_f32 v[102:103], v[106:107], v[102:103]
	v_cvt_pk_bf16_f32 v96, v96, v97
	v_cvt_pk_bf16_f32 v97, v98, v99
	v_cvt_pk_bf16_f32 v98, v100, v101
	v_cvt_pk_bf16_f32 v99, v102, v103
	global_store_dwordx4 v[112:113], v[96:99], off
	v_or_b32_e32 v112, 48, v138
	v_mad_i64_i32 v[114:115], s[4:5], v152, s55, v[120:121]
	v_ashrrev_i32_e32 v113, 31, v112
	v_fmamk_f32 v96, v193, 0x3a800000, v146
	v_rsq_f32_e32 v100, v96
	v_lshl_add_u64 v[96:97], v[114:115], 0, v[122:123]
	v_mul_f32_e32 v101, 0xbfb8aa3b, v100
	v_mul_f32_e32 v100, v100, v100
	v_mul_f32_e32 v84, v84, v101
	v_mul_f32_e32 v85, v85, v101
	v_mul_f32_e32 v86, v86, v101
	v_mul_f32_e32 v87, v87, v101
	v_mul_f32_e32 v80, v80, v101
	v_mul_f32_e32 v81, v81, v101
	v_mul_f32_e32 v82, v82, v101
	v_mul_f32_e32 v83, v83, v101
	v_rcp_f32_e32 v100, v100
	v_exp_f32_e32 v84, v84
	v_exp_f32_e32 v85, v85
	v_exp_f32_e32 v86, v86
	v_exp_f32_e32 v87, v87
	v_exp_f32_e32 v80, v80
	v_exp_f32_e32 v81, v81
	v_exp_f32_e32 v82, v82
	v_exp_f32_e32 v83, v83
	v_fma_f32 v84, v84, v100, v100
	v_fma_f32 v85, v85, v100, v100
	v_fma_f32 v86, v86, v100, v100
	v_fma_f32 v87, v87, v100, v100
	v_fma_f32 v101, v80, v100, v100
	v_fma_f32 v102, v81, v100, v100
	v_fma_f32 v103, v82, v100, v100
	v_fmac_f32_e32 v100, v83, v100
	v_rcp_f32_e32 v80, v84
	v_rcp_f32_e32 v81, v85
	v_rcp_f32_e32 v82, v86
	v_rcp_f32_e32 v83, v87
	v_rcp_f32_e32 v84, v101
	v_rcp_f32_e32 v85, v102
	v_rcp_f32_e32 v86, v103
	v_rcp_f32_e32 v87, v100
	v_pk_mul_f32 v[80:81], v[92:93], v[80:81]
	v_pk_mul_f32 v[82:83], v[94:95], v[82:83]
	v_pk_mul_f32 v[84:85], v[88:89], v[84:85]
	v_pk_mul_f32 v[86:87], v[90:91], v[86:87]
	v_cvt_pk_bf16_f32 v80, v80, v81
	v_cvt_pk_bf16_f32 v81, v82, v83
	v_cvt_pk_bf16_f32 v82, v84, v85
	v_cvt_pk_bf16_f32 v83, v86, v87
	global_store_dwordx4 v[96:97], v[80:83], off
	v_add_u32_e32 v96, 0x80, v138
	v_mad_i64_i32 v[98:99], s[4:5], v112, s55, v[120:121]
	v_ashrrev_i32_e32 v97, 31, v96
	v_fmamk_f32 v80, v197, 0x3a800000, v146
	v_rsq_f32_e32 v84, v80
	v_lshl_add_u64 v[80:81], v[98:99], 0, v[122:123]
	v_mul_f32_e32 v85, 0xbfb8aa3b, v84
	v_mul_f32_e32 v84, v84, v84
	v_mul_f32_e32 v68, v68, v85
	v_mul_f32_e32 v69, v69, v85
	v_mul_f32_e32 v70, v70, v85
	v_mul_f32_e32 v71, v71, v85
	v_mul_f32_e32 v64, v64, v85
	v_mul_f32_e32 v65, v65, v85
	v_mul_f32_e32 v66, v66, v85
	v_mul_f32_e32 v67, v67, v85
	v_rcp_f32_e32 v84, v84
	v_exp_f32_e32 v68, v68
	v_exp_f32_e32 v69, v69
	v_exp_f32_e32 v70, v70
	v_exp_f32_e32 v71, v71
	v_exp_f32_e32 v64, v64
	v_exp_f32_e32 v65, v65
	v_exp_f32_e32 v66, v66
	v_exp_f32_e32 v67, v67
	v_fma_f32 v68, v68, v84, v84
	v_fma_f32 v69, v69, v84, v84
	v_fma_f32 v70, v70, v84, v84
	v_fma_f32 v71, v71, v84, v84
	v_fma_f32 v85, v64, v84, v84
	v_fma_f32 v86, v65, v84, v84
	v_fma_f32 v87, v66, v84, v84
	v_fmac_f32_e32 v84, v67, v84
	v_rcp_f32_e32 v64, v68
	v_rcp_f32_e32 v65, v69
	v_rcp_f32_e32 v66, v70
	v_rcp_f32_e32 v67, v71
	v_rcp_f32_e32 v68, v85
	v_rcp_f32_e32 v69, v86
	v_rcp_f32_e32 v70, v87
	v_rcp_f32_e32 v71, v84
	v_pk_mul_f32 v[64:65], v[76:77], v[64:65]
	v_pk_mul_f32 v[66:67], v[78:79], v[66:67]
	v_pk_mul_f32 v[68:69], v[72:73], v[68:69]
	v_pk_mul_f32 v[70:71], v[74:75], v[70:71]
	v_cvt_pk_bf16_f32 v64, v64, v65
	v_cvt_pk_bf16_f32 v65, v66, v67
	v_cvt_pk_bf16_f32 v66, v68, v69
	v_cvt_pk_bf16_f32 v67, v70, v71
	global_store_dwordx4 v[80:81], v[64:67], off
	v_add_u32_e32 v80, 0x90, v138
	v_mad_i64_i32 v[82:83], s[4:5], v96, s55, v[120:121]
	v_ashrrev_i32_e32 v81, 31, v80
	v_fmamk_f32 v64, v201, 0x3a800000, v146
	v_rsq_f32_e32 v68, v64
	v_lshl_add_u64 v[64:65], v[82:83], 0, v[122:123]
	v_mul_f32_e32 v69, 0xbfb8aa3b, v68
	v_mul_f32_e32 v68, v68, v68
	v_mul_f32_e32 v52, v52, v69
	v_mul_f32_e32 v53, v53, v69
	v_mul_f32_e32 v54, v54, v69
	v_mul_f32_e32 v55, v55, v69
	v_mul_f32_e32 v48, v48, v69
	v_mul_f32_e32 v49, v49, v69
	v_mul_f32_e32 v50, v50, v69
	v_mul_f32_e32 v51, v51, v69
	v_rcp_f32_e32 v68, v68
	v_exp_f32_e32 v52, v52
	v_exp_f32_e32 v53, v53
	v_exp_f32_e32 v54, v54
	v_exp_f32_e32 v55, v55
	v_exp_f32_e32 v48, v48
	v_exp_f32_e32 v49, v49
	v_exp_f32_e32 v50, v50
	v_exp_f32_e32 v51, v51
	v_fma_f32 v52, v52, v68, v68
	v_fma_f32 v53, v53, v68, v68
	v_fma_f32 v54, v54, v68, v68
	v_fma_f32 v55, v55, v68, v68
	v_fma_f32 v69, v48, v68, v68
	v_fma_f32 v70, v49, v68, v68
	v_fma_f32 v71, v50, v68, v68
	v_fmac_f32_e32 v68, v51, v68
	v_rcp_f32_e32 v48, v52
	v_rcp_f32_e32 v49, v53
	v_rcp_f32_e32 v50, v54
	v_rcp_f32_e32 v51, v55
	v_rcp_f32_e32 v52, v69
	v_rcp_f32_e32 v53, v70
	v_rcp_f32_e32 v54, v71
	v_rcp_f32_e32 v55, v68
	v_pk_mul_f32 v[48:49], v[60:61], v[48:49]
	v_pk_mul_f32 v[50:51], v[62:63], v[50:51]
	v_pk_mul_f32 v[52:53], v[56:57], v[52:53]
	v_pk_mul_f32 v[54:55], v[58:59], v[54:55]
	v_cvt_pk_bf16_f32 v48, v48, v49
	v_cvt_pk_bf16_f32 v49, v50, v51
	v_cvt_pk_bf16_f32 v50, v52, v53
	v_cvt_pk_bf16_f32 v51, v54, v55
	global_store_dwordx4 v[64:65], v[48:51], off
	v_add_u32_e32 v64, 0xa0, v138
	v_mad_i64_i32 v[66:67], s[4:5], v80, s55, v[120:121]
	v_ashrrev_i32_e32 v65, 31, v64
	v_fmamk_f32 v48, v205, 0x3a800000, v146
	v_rsq_f32_e32 v52, v48
	v_lshl_add_u64 v[48:49], v[66:67], 0, v[122:123]
	v_mul_f32_e32 v53, 0xbfb8aa3b, v52
	v_mul_f32_e32 v52, v52, v52
	v_mul_f32_e32 v36, v36, v53
	v_mul_f32_e32 v37, v37, v53
	v_mul_f32_e32 v38, v38, v53
	v_mul_f32_e32 v39, v39, v53
	v_mul_f32_e32 v32, v32, v53
	v_mul_f32_e32 v33, v33, v53
	v_mul_f32_e32 v34, v34, v53
	v_mul_f32_e32 v35, v35, v53
	v_rcp_f32_e32 v52, v52
	v_exp_f32_e32 v36, v36
	v_exp_f32_e32 v37, v37
	v_exp_f32_e32 v38, v38
	v_exp_f32_e32 v39, v39
	v_exp_f32_e32 v32, v32
	v_exp_f32_e32 v33, v33
	v_exp_f32_e32 v34, v34
	v_exp_f32_e32 v35, v35
	v_fma_f32 v36, v36, v52, v52
	v_fma_f32 v37, v37, v52, v52
	v_fma_f32 v38, v38, v52, v52
	v_fma_f32 v39, v39, v52, v52
	v_fma_f32 v53, v32, v52, v52
	v_fma_f32 v54, v33, v52, v52
	v_fma_f32 v55, v34, v52, v52
	v_fmac_f32_e32 v52, v35, v52
	v_rcp_f32_e32 v32, v36
	v_rcp_f32_e32 v33, v37
	v_rcp_f32_e32 v34, v38
	v_rcp_f32_e32 v35, v39
	v_rcp_f32_e32 v36, v53
	v_rcp_f32_e32 v37, v54
	v_rcp_f32_e32 v38, v55
	v_rcp_f32_e32 v39, v52
	v_pk_mul_f32 v[32:33], v[44:45], v[32:33]
	v_pk_mul_f32 v[34:35], v[46:47], v[34:35]
	v_pk_mul_f32 v[36:37], v[40:41], v[36:37]
	v_pk_mul_f32 v[38:39], v[42:43], v[38:39]
	v_cvt_pk_bf16_f32 v32, v32, v33
	v_cvt_pk_bf16_f32 v33, v34, v35
	v_cvt_pk_bf16_f32 v34, v36, v37
	v_cvt_pk_bf16_f32 v35, v38, v39
	global_store_dwordx4 v[48:49], v[32:35], off
	v_add_u32_e32 v48, 0xb0, v138
	v_mad_i64_i32 v[50:51], s[4:5], v64, s55, v[120:121]
	v_ashrrev_i32_e32 v49, 31, v48
	v_lshlrev_b64 v[34:35], 6, v[48:49]
	v_lshl_add_u64 v[34:35], s[8:9], 0, v[34:35]
	v_fmamk_f32 v32, v209, 0x3a800000, v146
	v_rsq_f32_e32 v36, v32
	v_lshl_add_u64 v[32:33], v[50:51], 0, v[122:123]
	v_mul_f32_e32 v37, 0xbfb8aa3b, v36
	v_mul_f32_e32 v36, v36, v36
	v_mul_f32_e32 v20, v20, v37
	v_mul_f32_e32 v21, v21, v37
	v_mul_f32_e32 v22, v22, v37
	v_mul_f32_e32 v23, v23, v37
	v_mul_f32_e32 v16, v16, v37
	v_mul_f32_e32 v17, v17, v37
	v_mul_f32_e32 v18, v18, v37
	v_mul_f32_e32 v19, v19, v37
	v_rcp_f32_e32 v36, v36
	v_exp_f32_e32 v20, v20
	v_exp_f32_e32 v21, v21
	v_exp_f32_e32 v22, v22
	v_exp_f32_e32 v23, v23
	v_exp_f32_e32 v16, v16
	v_exp_f32_e32 v17, v17
	v_exp_f32_e32 v18, v18
	v_exp_f32_e32 v19, v19
	v_fma_f32 v20, v20, v36, v36
	v_fma_f32 v21, v21, v36, v36
	v_fma_f32 v22, v22, v36, v36
	v_fma_f32 v23, v23, v36, v36
	v_fma_f32 v37, v16, v36, v36
	v_fma_f32 v38, v17, v36, v36
	v_fma_f32 v39, v18, v36, v36
	v_fmac_f32_e32 v36, v19, v36
	v_rcp_f32_e32 v16, v20
	v_rcp_f32_e32 v17, v21
	v_rcp_f32_e32 v18, v22
	v_rcp_f32_e32 v19, v23
	v_rcp_f32_e32 v20, v37
	v_rcp_f32_e32 v21, v38
	v_rcp_f32_e32 v22, v39
	v_rcp_f32_e32 v23, v36
	v_pk_mul_f32 v[16:17], v[28:29], v[16:17]
	v_pk_mul_f32 v[18:19], v[30:31], v[18:19]
	v_pk_mul_f32 v[20:21], v[24:25], v[20:21]
	v_pk_mul_f32 v[22:23], v[26:27], v[22:23]
	v_cvt_pk_bf16_f32 v16, v16, v17
	v_cvt_pk_bf16_f32 v17, v18, v19
	v_cvt_pk_bf16_f32 v18, v20, v21
	v_cvt_pk_bf16_f32 v19, v22, v23
	global_store_dwordx4 v[32:33], v[16:19], off
	s_nop 1
	v_fmamk_f32 v16, v213, 0x3a800000, v146
	v_rsq_f32_e32 v18, v16
	v_mad_i64_i32 v[16:17], s[4:5], v48, s55, v[120:121]
	v_lshl_add_u64 v[16:17], v[16:17], 0, v[122:123]
	v_mul_f32_e32 v19, 0xbfb8aa3b, v18
	v_mul_f32_e32 v18, v18, v18
	v_mul_f32_e32 v4, v4, v19
	v_mul_f32_e32 v5, v5, v19
	v_mul_f32_e32 v6, v6, v19
	v_mul_f32_e32 v7, v7, v19
	v_mul_f32_e32 v0, v0, v19
	v_mul_f32_e32 v1, v1, v19
	v_mul_f32_e32 v2, v2, v19
	v_mul_f32_e32 v3, v3, v19
	v_rcp_f32_e32 v18, v18
	v_exp_f32_e32 v4, v4
	v_exp_f32_e32 v5, v5
	v_exp_f32_e32 v6, v6
	v_exp_f32_e32 v7, v7
	v_exp_f32_e32 v0, v0
	v_exp_f32_e32 v1, v1
	v_exp_f32_e32 v2, v2
	v_exp_f32_e32 v3, v3
	v_fma_f32 v4, v4, v18, v18
	v_fma_f32 v5, v5, v18, v18
	v_fma_f32 v6, v6, v18, v18
	v_fma_f32 v7, v7, v18, v18
	v_fma_f32 v19, v0, v18, v18
	v_fma_f32 v20, v1, v18, v18
	v_fma_f32 v21, v2, v18, v18
	v_fmac_f32_e32 v18, v3, v18
	v_rcp_f32_e32 v0, v4
	v_rcp_f32_e32 v1, v5
	v_rcp_f32_e32 v2, v6
	v_rcp_f32_e32 v3, v7
	v_rcp_f32_e32 v4, v19
	v_rcp_f32_e32 v5, v20
	v_rcp_f32_e32 v6, v21
	v_rcp_f32_e32 v7, v18
	v_pk_mul_f32 v[0:1], v[12:13], v[0:1]
	v_pk_mul_f32 v[2:3], v[14:15], v[2:3]
	v_pk_mul_f32 v[4:5], v[8:9], v[4:5]
	v_pk_mul_f32 v[6:7], v[10:11], v[6:7]
	v_cvt_pk_bf16_f32 v0, v0, v1
	v_cvt_pk_bf16_f32 v1, v2, v3
	v_cvt_pk_bf16_f32 v2, v4, v5
	v_cvt_pk_bf16_f32 v3, v6, v7
	s_mov_b64 s[4:5], -1
	global_store_dwordx4 v[16:17], v[0:3], off
	s_cbranch_scc1 .LBB0_1457
	s_andn2_b64 vcc, exec, s[6:7]
	s_cbranch_vccnz .LBB0_1456
	s_barrier
	s_branch .LBB0_1456

.LBB0_1657:
	v_and_b32_e32 v232, 48, v146
	v_mul_u32_u24_e32 v232, 3, v232
	v_sub_u32_e32 v232, 0, v232
	v_ashrrev_i32_e32 v233, 31, v232
	v_lshl_add_u32 v140, s26, 8, v144
	v_ashrrev_i32_e32 v141, 31, v140
	v_mbcnt_lo_u32_b32 v188, -1, 0
	v_mbcnt_hi_u32_b32 v188, -1, v188
	v_lshlrev_b64 v[236:237], 6, v[140:141]
	v_lshl_add_u64 v[236:237], s[6:7], 0, v[236:237]
	v_and_b32_e32 v238, 48, v188
	v_mov_b32_e32 v239, 0
	s_mov_b64 s[98:99], 0x2000
	v_lshl_add_u64 v[236:237], v[236:237], 0, v[238:239]
	v_lshl_add_u64 v[238:239], v[236:237], 0, s[98:99]
	global_load_dwordx4 v[152:155], v[236:237], off
	global_load_dwordx4 v[156:159], v[236:237], off offset:1024
	global_load_dwordx4 v[160:163], v[236:237], off offset:2048
	global_load_dwordx4 v[164:167], v[236:237], off offset:3072
	global_load_dwordx4 v[192:195], v[238:239], off
	global_load_dwordx4 v[196:199], v[238:239], off offset:1024
	global_load_dwordx4 v[200:203], v[238:239], off offset:2048
	global_load_dwordx4 v[204:207], v[238:239], off offset:3072
	v_and_b32_e32 v189, 15, v188
	v_lshlrev_b32_e32 v189, 2, v189
	v_add_u32_e32 v190, 64, v189
	v_add_u32_e32 v191, 128, v189
	v_add_u32_e32 v188, 192, v189
	v_lshlrev_b64 v[138:139], 6, v[140:141]
	v_lshl_add_u64 v[138:139], s[6:7], 0, v[138:139]
	v_lshl_or_b32 v142, s24, 8, v146
	v_ashrrev_i32_e32 v143, 31, v142
	v_lshlrev_b64 v[168:169], 11, v[140:141]
	v_lshlrev_b64 v[138:139], 1, v[142:143]
	v_lshl_add_u64 v[170:171], s[8:9], 0, v[168:169]
	v_lshl_add_u64 v[172:173], s[0:1], 0, v[168:169]
	v_lshl_add_u64 v[176:177], v[170:171], 0, v[138:139]
	v_lshl_add_u64 v[180:181], v[172:173], 0, v[138:139]
	global_load_dwordx4 v[168:171], v[176:177], off
	global_load_dwordx4 v[172:175], v[180:181], off
	s_nop 0
	global_load_dwordx4 v[176:179], v[176:177], off offset:16
	s_nop 0
	global_load_dwordx4 v[180:183], v[180:181], off offset:16
	s_cmp_eq_u32 s25, s47
	s_mov_b64 s[24:25], -1
	s_waitcnt vmcnt(0)
	v_add_f32_e32 v152, v152, v153
	v_add_f32_e32 v154, v154, v155
	v_add_f32_e32 v156, v156, v157
	v_add_f32_e32 v158, v158, v159
	v_add_f32_e32 v160, v160, v161
	v_add_f32_e32 v162, v162, v163
	v_add_f32_e32 v164, v164, v165
	v_add_f32_e32 v166, v166, v167
	v_add_f32_e32 v192, v192, v193
	v_add_f32_e32 v194, v194, v195
	v_add_f32_e32 v196, v196, v197
	v_add_f32_e32 v198, v198, v199
	v_add_f32_e32 v200, v200, v201
	v_add_f32_e32 v202, v202, v203
	v_add_f32_e32 v204, v204, v205
	v_add_f32_e32 v206, v206, v207
	v_add_f32_e32 v152, v152, v154
	v_add_f32_e32 v156, v156, v158
	v_add_f32_e32 v160, v160, v162
	v_add_f32_e32 v164, v164, v166
	v_add_f32_e32 v192, v192, v194
	v_add_f32_e32 v196, v196, v198
	v_add_f32_e32 v200, v200, v202
	v_add_f32_e32 v204, v204, v206
	ds_bpermute_b32 v153, v189, v152
	ds_bpermute_b32 v157, v189, v156
	ds_bpermute_b32 v161, v189, v160
	ds_bpermute_b32 v165, v189, v164
	ds_bpermute_b32 v193, v189, v192
	ds_bpermute_b32 v197, v189, v196
	ds_bpermute_b32 v201, v189, v200
	ds_bpermute_b32 v205, v189, v204
	s_waitcnt lgkmcnt(0)
	ds_bpermute_b32 v154, v190, v152
	ds_bpermute_b32 v158, v190, v156
	ds_bpermute_b32 v162, v190, v160
	ds_bpermute_b32 v166, v190, v164
	ds_bpermute_b32 v194, v190, v192
	ds_bpermute_b32 v198, v190, v196
	ds_bpermute_b32 v202, v190, v200
	ds_bpermute_b32 v206, v190, v204
	s_waitcnt lgkmcnt(0)
	v_add_f32_e32 v153, v153, v154
	v_add_f32_e32 v157, v157, v158
	v_add_f32_e32 v161, v161, v162
	v_add_f32_e32 v165, v165, v166
	v_add_f32_e32 v193, v193, v194
	v_add_f32_e32 v197, v197, v198
	v_add_f32_e32 v201, v201, v202
	v_add_f32_e32 v205, v205, v206
	ds_bpermute_b32 v154, v191, v152
	ds_bpermute_b32 v158, v191, v156
	ds_bpermute_b32 v162, v191, v160
	ds_bpermute_b32 v166, v191, v164
	ds_bpermute_b32 v194, v191, v192
	ds_bpermute_b32 v198, v191, v196
	ds_bpermute_b32 v202, v191, v200
	ds_bpermute_b32 v206, v191, v204
	s_waitcnt lgkmcnt(0)
	v_add_f32_e32 v153, v153, v154
	v_add_f32_e32 v157, v157, v158
	v_add_f32_e32 v161, v161, v162
	v_add_f32_e32 v165, v165, v166
	v_add_f32_e32 v193, v193, v194
	v_add_f32_e32 v197, v197, v198
	v_add_f32_e32 v201, v201, v202
	v_add_f32_e32 v205, v205, v206
	ds_bpermute_b32 v154, v188, v152
	ds_bpermute_b32 v158, v188, v156
	ds_bpermute_b32 v162, v188, v160
	ds_bpermute_b32 v166, v188, v164
	ds_bpermute_b32 v194, v188, v192
	ds_bpermute_b32 v198, v188, v196
	ds_bpermute_b32 v202, v188, v200
	ds_bpermute_b32 v206, v188, v204
	s_waitcnt lgkmcnt(0)
	v_add_f32_e32 v208, v153, v154
	v_add_f32_e32 v209, v157, v158
	v_add_f32_e32 v210, v161, v162
	v_add_f32_e32 v211, v165, v166
	v_add_f32_e32 v212, v193, v194
	v_add_f32_e32 v213, v197, v198
	v_add_f32_e32 v214, v201, v202
	v_add_f32_e32 v215, v205, v206
	v_lshlrev_b32_e32 v158, 16, v168
	v_and_b32_e32 v159, 0xffff0000, v168
	v_fmamk_f32 v151, v208, 0x3a800000, v150
	v_and_b32_e32 v153, 0xffff0000, v176
	v_lshlrev_b32_e32 v162, 16, v172
	v_rsq_f32_e32 v151, v151
	v_lshlrev_b32_e32 v152, 16, v176
	v_and_b32_e32 v163, 0xffff0000, v172
	v_lshlrev_b32_e32 v164, 16, v169
	v_mul_f32_e32 v151, 0xbfb8aa3b, v151
	v_mul_f32_e32 v127, v127, v151
	v_mul_f32_e32 v117, v117, v151
	v_mul_f32_e32 v112, v112, v151
	v_mul_f32_e32 v124, v124, v151
	v_mul_f32_e32 v121, v121, v151
	v_mul_f32_e32 v122, v122, v151
	v_exp_f32_e32 v127, v127
	v_exp_f32_e32 v117, v117
	v_exp_f32_e32 v112, v112
	v_mul_f32_e32 v113, v113, v151
	v_mul_f32_e32 v120, v120, v151
	v_mul_f32_e32 v123, v123, v151
	v_exp_f32_e32 v124, v124
	v_exp_f32_e32 v121, v121
	v_exp_f32_e32 v122, v122
	v_exp_f32_e32 v113, v113
	v_exp_f32_e32 v120, v120
	v_exp_f32_e32 v123, v123
	v_add_f32_e32 v127, 1.0, v127
	v_add_f32_e32 v176, 1.0, v117
	v_add_f32_e32 v112, 1.0, v112
	v_mul_f32_e32 v125, v125, v151
	v_mul_f32_e32 v126, v126, v151
	v_add_f32_e32 v124, 1.0, v124
	v_add_f32_e32 v156, 1.0, v121
	v_add_f32_e32 v157, 1.0, v122
	v_rcp_f32_e32 v117, v127
	v_rcp_f32_e32 v127, v176
	v_rcp_f32_e32 v176, v112
	v_add_f32_e32 v112, 1.0, v113
	v_mul_f32_e32 v116, v116, v151
	v_exp_f32_e32 v125, v125
	v_exp_f32_e32 v126, v126
	v_add_f32_e32 v155, 1.0, v120
	v_add_f32_e32 v160, 1.0, v123
	v_rcp_f32_e32 v120, v124
	v_rcp_f32_e32 v123, v156
	v_rcp_f32_e32 v124, v157
	v_lshlrev_b32_e32 v156, 16, v177
	v_and_b32_e32 v157, 0xffff0000, v177
	v_rcp_f32_e32 v177, v112
	v_mul_f32_e32 v112, v114, v151
	v_mul_f32_e32 v118, v118, v151
	v_exp_f32_e32 v116, v116
	v_mul_f32_e32 v119, v119, v151
	v_exp_f32_e32 v112, v112
	v_mul_f32_e32 v113, v115, v151
	v_exp_f32_e32 v118, v118
	v_exp_f32_e32 v119, v119
	v_exp_f32_e32 v113, v113
	v_add_f32_e32 v125, 1.0, v125
	v_add_f32_e32 v126, 1.0, v126
	v_add_f32_e32 v161, 1.0, v116
	v_rcp_f32_e32 v121, v125
	v_rcp_f32_e32 v116, v126
	v_add_f32_e32 v112, 1.0, v112
	v_rcp_f32_e32 v122, v155
	v_rcp_f32_e32 v125, v160
	v_add_f32_e32 v118, 1.0, v118
	v_add_f32_e32 v119, 1.0, v119
	v_rcp_f32_e32 v186, v112
	v_add_f32_e32 v112, 1.0, v113
	v_rcp_f32_e32 v126, v161
	v_rcp_f32_e32 v118, v118
	v_rcp_f32_e32 v119, v119
	v_rcp_f32_e32 v187, v112
	v_lshlrev_b64 v[112:113], 12, v[140:141]
	v_and_b32_e32 v165, 0xffff0000, v169
	v_lshlrev_b32_e32 v166, 16, v173
	v_and_b32_e32 v167, 0xffff0000, v173
	v_lshl_add_u64 v[114:115], s[84:85], 0, v[112:113]
	v_lshlrev_b64 v[112:113], 2, v[142:143]
	v_lshlrev_b32_e32 v168, 16, v170
	v_and_b32_e32 v169, 0xffff0000, v170
	v_lshlrev_b32_e32 v172, 16, v174
	v_and_b32_e32 v173, 0xffff0000, v174
	v_lshlrev_b32_e32 v170, 16, v171
	v_and_b32_e32 v171, 0xffff0000, v171
	v_lshlrev_b32_e32 v174, 16, v175
	v_and_b32_e32 v175, 0xffff0000, v175
	v_lshl_add_u64 v[142:143], v[114:115], 0, v[112:113]
	v_pk_fma_f32 v[218:219], v[116:117], v[164:165], v[166:167]
	v_pk_fma_f32 v[216:217], v[120:121], v[158:159], v[162:163]
	v_lshlrev_b32_e32 v154, 16, v180
	v_and_b32_e32 v155, 0xffff0000, v180
	v_lshlrev_b32_e32 v160, 16, v181
	v_and_b32_e32 v161, 0xffff0000, v181
	v_lshlrev_b32_e32 v180, 16, v178
	v_and_b32_e32 v181, 0xffff0000, v178
	v_pk_fma_f32 v[222:223], v[124:125], v[170:171], v[174:175]
	v_pk_fma_f32 v[220:221], v[122:123], v[168:169], v[172:173]
	v_lshlrev_b32_e32 v184, 16, v182
	v_and_b32_e32 v185, 0xffff0000, v182
	v_lshlrev_b32_e32 v178, 16, v179
	v_and_b32_e32 v179, 0xffff0000, v179
	v_lshlrev_b32_e32 v182, 16, v183
	v_and_b32_e32 v183, 0xffff0000, v183
	s_nop 1
	v_pk_fma_f32 v[226:227], v[118:119], v[156:157], v[160:161]
	v_pk_fma_f32 v[224:225], v[126:127], v[152:153], v[154:155]
	v_or_b32_e32 v126, 16, v140
	v_ashrrev_i32_e32 v127, 31, v126
	s_nop 0
	v_pk_fma_f32 v[230:231], v[186:187], v[178:179], v[182:183]
	v_pk_fma_f32 v[228:229], v[176:177], v[180:181], v[184:185]
	s_nop 1
	v_permlane16_swap_b32_e32 v216, v220
	v_permlane16_swap_b32_e32 v217, v221
	v_permlane16_swap_b32_e32 v218, v222
	v_permlane16_swap_b32_e32 v219, v223
	v_permlane16_swap_b32_e32 v224, v228
	v_permlane16_swap_b32_e32 v225, v229
	v_permlane16_swap_b32_e32 v226, v230
	v_permlane16_swap_b32_e32 v227, v231
	v_permlane32_swap_b32_e32 v216, v224
	v_permlane32_swap_b32_e32 v217, v225
	v_permlane32_swap_b32_e32 v218, v226
	v_permlane32_swap_b32_e32 v219, v227
	v_permlane32_swap_b32_e32 v220, v228
	v_permlane32_swap_b32_e32 v221, v229
	v_permlane32_swap_b32_e32 v222, v230
	v_permlane32_swap_b32_e32 v223, v231
	v_lshl_add_u64 v[234:235], v[142:143], 0, v[232:233]
	global_store_dwordx4 v[234:235], v[216:219], off
	global_store_dwordx4 v[234:235], v[220:223], off offset:64
	global_store_dwordx4 v[234:235], v[224:227], off offset:128
	global_store_dwordx4 v[234:235], v[228:231], off offset:192
	s_nop 1
	v_lshlrev_b64 v[114:115], 6, v[126:127]
	v_lshl_add_u64 v[142:143], s[6:7], 0, v[114:115]
	v_lshlrev_b64 v[142:143], 11, v[126:127]
	v_lshl_add_u64 v[156:157], s[8:9], 0, v[142:143]
	v_lshl_add_u64 v[142:143], s[0:1], 0, v[142:143]
	v_lshl_add_u64 v[164:165], v[156:157], 0, v[138:139]
	v_lshl_add_u64 v[142:143], v[142:143], 0, v[138:139]
	global_load_dwordx4 v[156:159], v[164:165], off
	global_load_dwordx4 v[160:163], v[142:143], off
	s_nop 0
	global_load_dwordx4 v[164:167], v[164:165], off offset:16
	s_nop 0
	global_load_dwordx4 v[168:171], v[142:143], off offset:16
	s_waitcnt vmcnt(7)
	s_waitcnt vmcnt(6)
	s_waitcnt vmcnt(5)
	s_waitcnt vmcnt(4)
	s_waitcnt vmcnt(2)
	v_lshlrev_b32_e32 v124, 16, v162
	v_and_b32_e32 v125, 0xffff0000, v162
	v_fmamk_f32 v114, v209, 0x3a800000, v150
	v_lshlrev_b32_e32 v152, 16, v163
	v_and_b32_e32 v153, 0xffff0000, v163
	v_rsq_f32_e32 v116, v114
	v_lshlrev_b32_e32 v114, 16, v156
	v_and_b32_e32 v115, 0xffff0000, v156
	v_lshlrev_b32_e32 v118, 16, v157
	v_mul_f32_e32 v141, 0xbfb8aa3b, v116
	v_mul_f32_e32 v109, v109, v141
	v_mul_f32_e32 v96, v96, v141
	v_exp_f32_e32 v109, v109
	v_exp_f32_e32 v96, v96
	v_mul_f32_e32 v97, v97, v141
	v_exp_f32_e32 v97, v97
	v_add_f32_e32 v109, 1.0, v109
	v_add_f32_e32 v96, 1.0, v96
	v_mul_f32_e32 v108, v108, v141
	v_mul_f32_e32 v110, v110, v141
	v_rcp_f32_e32 v117, v109
	v_mul_f32_e32 v109, v111, v141
	v_rcp_f32_e32 v162, v96
	v_add_f32_e32 v96, 1.0, v97
	v_exp_f32_e32 v116, v108
	v_exp_f32_e32 v110, v110
	v_exp_f32_e32 v111, v109
	v_mul_f32_e32 v104, v104, v141
	v_mul_f32_e32 v105, v105, v141
	v_mul_f32_e32 v106, v106, v141
	v_mul_f32_e32 v107, v107, v141
	v_rcp_f32_e32 v163, v96
	v_mul_f32_e32 v96, v98, v141
	v_exp_f32_e32 v104, v104
	v_exp_f32_e32 v105, v105
	v_exp_f32_e32 v106, v106
	v_exp_f32_e32 v107, v107
	v_mul_f32_e32 v100, v100, v141
	v_mul_f32_e32 v101, v101, v141
	v_mul_f32_e32 v102, v102, v141
	v_mul_f32_e32 v103, v103, v141
	v_exp_f32_e32 v96, v96
	v_mul_f32_e32 v97, v99, v141
	v_exp_f32_e32 v100, v100
	v_exp_f32_e32 v101, v101
	v_exp_f32_e32 v102, v102
	v_exp_f32_e32 v103, v103
	v_exp_f32_e32 v97, v97
	v_add_f32_e32 v116, 1.0, v116
	v_add_f32_e32 v110, 1.0, v110
	v_add_f32_e32 v111, 1.0, v111
	v_rcp_f32_e32 v116, v116
	v_rcp_f32_e32 v110, v110
	v_rcp_f32_e32 v111, v111
	v_add_f32_e32 v104, 1.0, v104
	v_add_f32_e32 v105, 1.0, v105
	v_add_f32_e32 v106, 1.0, v106
	v_add_f32_e32 v107, 1.0, v107
	v_add_f32_e32 v96, 1.0, v96
	v_rcp_f32_e32 v104, v104
	v_rcp_f32_e32 v105, v105
	v_rcp_f32_e32 v106, v106
	v_rcp_f32_e32 v107, v107
	v_add_f32_e32 v100, 1.0, v100
	v_add_f32_e32 v101, 1.0, v101
	v_add_f32_e32 v102, 1.0, v102
	v_add_f32_e32 v103, 1.0, v103
	v_rcp_f32_e32 v172, v96
	v_add_f32_e32 v96, 1.0, v97
	v_rcp_f32_e32 v100, v100
	v_rcp_f32_e32 v101, v101
	v_rcp_f32_e32 v102, v102
	v_rcp_f32_e32 v103, v103
	v_rcp_f32_e32 v173, v96
	v_lshlrev_b64 v[96:97], 12, v[126:127]
	v_lshlrev_b32_e32 v108, 16, v160
	v_and_b32_e32 v109, 0xffff0000, v160
	v_and_b32_e32 v119, 0xffff0000, v157
	v_lshlrev_b32_e32 v120, 16, v161
	v_and_b32_e32 v121, 0xffff0000, v161
	v_lshl_add_u64 v[96:97], s[84:85], 0, v[96:97]
	v_lshlrev_b32_e32 v122, 16, v158
	v_and_b32_e32 v123, 0xffff0000, v158
	v_lshlrev_b32_e32 v142, 16, v159
	v_and_b32_e32 v143, 0xffff0000, v159
	v_lshl_add_u64 v[126:127], v[96:97], 0, v[112:113]
	v_pk_fma_f32 v[218:219], v[110:111], v[118:119], v[120:121]
	v_pk_fma_f32 v[216:217], v[116:117], v[114:115], v[108:109]
	s_waitcnt vmcnt(1)
	v_lshlrev_b32_e32 v154, 16, v164
	v_and_b32_e32 v155, 0xffff0000, v164
	s_waitcnt vmcnt(0)
	v_lshlrev_b32_e32 v156, 16, v168
	v_and_b32_e32 v157, 0xffff0000, v168
	v_lshlrev_b32_e32 v158, 16, v165
	v_and_b32_e32 v159, 0xffff0000, v165
	v_lshlrev_b32_e32 v160, 16, v169
	v_and_b32_e32 v161, 0xffff0000, v169
	v_lshlrev_b32_e32 v164, 16, v166
	v_and_b32_e32 v165, 0xffff0000, v166
	v_pk_fma_f32 v[222:223], v[106:107], v[142:143], v[152:153]
	v_pk_fma_f32 v[220:221], v[104:105], v[122:123], v[124:125]
	v_lshlrev_b32_e32 v168, 16, v170
	v_and_b32_e32 v169, 0xffff0000, v170
	v_lshlrev_b32_e32 v166, 16, v167
	v_and_b32_e32 v167, 0xffff0000, v167
	v_lshlrev_b32_e32 v170, 16, v171
	v_and_b32_e32 v171, 0xffff0000, v171
	s_nop 1
	v_pk_fma_f32 v[226:227], v[102:103], v[158:159], v[160:161]
	v_pk_fma_f32 v[224:225], v[100:101], v[154:155], v[156:157]
	s_nop 1
	v_pk_fma_f32 v[230:231], v[172:173], v[166:167], v[170:171]
	v_pk_fma_f32 v[228:229], v[162:163], v[164:165], v[168:169]
	s_nop 1
	v_permlane16_swap_b32_e32 v216, v220
	v_permlane16_swap_b32_e32 v217, v221
	v_permlane16_swap_b32_e32 v218, v222
	v_permlane16_swap_b32_e32 v219, v223
	v_permlane16_swap_b32_e32 v224, v228
	v_permlane16_swap_b32_e32 v225, v229
	v_permlane16_swap_b32_e32 v226, v230
	v_permlane16_swap_b32_e32 v227, v231
	v_permlane32_swap_b32_e32 v216, v224
	v_permlane32_swap_b32_e32 v217, v225
	v_permlane32_swap_b32_e32 v218, v226
	v_permlane32_swap_b32_e32 v219, v227
	v_permlane32_swap_b32_e32 v220, v228
	v_permlane32_swap_b32_e32 v221, v229
	v_permlane32_swap_b32_e32 v222, v230
	v_permlane32_swap_b32_e32 v223, v231
	v_lshl_add_u64 v[234:235], v[126:127], 0, v[232:233]
	global_store_dwordx4 v[234:235], v[216:219], off
	global_store_dwordx4 v[234:235], v[220:223], off offset:64
	global_store_dwordx4 v[234:235], v[224:227], off offset:128
	global_store_dwordx4 v[234:235], v[228:231], off offset:192
	v_or_b32_e32 v126, 32, v140
	v_ashrrev_i32_e32 v127, 31, v126
	v_lshlrev_b64 v[96:97], 6, v[126:127]
	v_lshl_add_u64 v[108:109], s[6:7], 0, v[96:97]
	s_nop 0
	v_lshlrev_b64 v[114:115], 11, v[126:127]
	v_lshl_add_u64 v[116:117], s[8:9], 0, v[114:115]
	v_lshl_add_u64 v[122:123], v[116:117], 0, v[138:139]
	v_lshl_add_u64 v[118:119], s[0:1], 0, v[114:115]
	global_load_dwordx4 v[114:117], v[122:123], off
	v_lshl_add_u64 v[142:143], v[118:119], 0, v[138:139]
	global_load_dwordx4 v[118:121], v[142:143], off
	s_nop 0
	global_load_dwordx4 v[122:125], v[122:123], off offset:16
	s_nop 0
	global_load_dwordx4 v[152:155], v[142:143], off offset:16
	s_waitcnt vmcnt(7)
	s_waitcnt vmcnt(6)
	s_waitcnt vmcnt(5)
	s_waitcnt vmcnt(4)
	s_waitcnt vmcnt(3)
	v_lshlrev_b32_e32 v100, 16, v115
	v_and_b32_e32 v101, 0xffff0000, v115
	v_fmamk_f32 v96, v210, 0x3a800000, v150
	s_waitcnt vmcnt(1)
	v_and_b32_e32 v115, 0xffff0000, v122
	v_lshlrev_b32_e32 v98, 16, v118
	v_rsq_f32_e32 v96, v96
	v_and_b32_e32 v99, 0xffff0000, v118
	v_lshlrev_b32_e32 v102, 16, v119
	v_and_b32_e32 v103, 0xffff0000, v119
	v_mul_f32_e32 v141, 0xbfb8aa3b, v96
	v_mul_f32_e32 v80, v80, v141
	v_exp_f32_e32 v80, v80
	v_mul_f32_e32 v81, v81, v141
	v_exp_f32_e32 v81, v81
	v_mul_f32_e32 v92, v92, v141
	v_add_f32_e32 v80, 1.0, v80
	v_mul_f32_e32 v93, v93, v141
	v_lshlrev_b32_e32 v96, 16, v114
	v_and_b32_e32 v97, 0xffff0000, v114
	v_mul_f32_e32 v94, v94, v141
	v_mul_f32_e32 v95, v95, v141
	v_lshlrev_b32_e32 v114, 16, v122
	v_rcp_f32_e32 v122, v80
	v_add_f32_e32 v80, 1.0, v81
	v_exp_f32_e32 v92, v92
	v_exp_f32_e32 v93, v93
	v_exp_f32_e32 v94, v94
	v_exp_f32_e32 v95, v95
	v_mul_f32_e32 v88, v88, v141
	v_mul_f32_e32 v89, v89, v141
	v_mul_f32_e32 v90, v90, v141
	v_mul_f32_e32 v91, v91, v141
	v_lshlrev_b32_e32 v118, 16, v123
	v_and_b32_e32 v119, 0xffff0000, v123
	v_rcp_f32_e32 v123, v80
	v_mul_f32_e32 v80, v82, v141
	v_exp_f32_e32 v88, v88
	v_exp_f32_e32 v89, v89
	v_exp_f32_e32 v90, v90
	v_exp_f32_e32 v91, v91
	v_mul_f32_e32 v84, v84, v141
	v_mul_f32_e32 v85, v85, v141
	v_mul_f32_e32 v86, v86, v141
	v_mul_f32_e32 v87, v87, v141
	v_exp_f32_e32 v80, v80
	v_mul_f32_e32 v81, v83, v141
	v_exp_f32_e32 v84, v84
	v_exp_f32_e32 v85, v85
	v_exp_f32_e32 v86, v86
	v_exp_f32_e32 v87, v87
	v_exp_f32_e32 v81, v81
	v_add_f32_e32 v92, 1.0, v92
	v_add_f32_e32 v93, 1.0, v93
	v_add_f32_e32 v94, 1.0, v94
	v_add_f32_e32 v95, 1.0, v95
	v_rcp_f32_e32 v92, v92
	v_rcp_f32_e32 v93, v93
	v_rcp_f32_e32 v94, v94
	v_rcp_f32_e32 v95, v95
	v_add_f32_e32 v88, 1.0, v88
	v_add_f32_e32 v89, 1.0, v89
	v_add_f32_e32 v90, 1.0, v90
	v_add_f32_e32 v91, 1.0, v91
	v_add_f32_e32 v80, 1.0, v80
	v_rcp_f32_e32 v88, v88
	v_rcp_f32_e32 v89, v89
	v_rcp_f32_e32 v90, v90
	v_rcp_f32_e32 v91, v91
	v_add_f32_e32 v84, 1.0, v84
	v_add_f32_e32 v85, 1.0, v85
	v_add_f32_e32 v86, 1.0, v86
	v_add_f32_e32 v87, 1.0, v87
	v_rcp_f32_e32 v156, v80
	v_add_f32_e32 v80, 1.0, v81
	v_rcp_f32_e32 v84, v84
	v_rcp_f32_e32 v85, v85
	v_rcp_f32_e32 v86, v86
	v_rcp_f32_e32 v87, v87
	v_rcp_f32_e32 v157, v80
	v_lshlrev_b64 v[80:81], 12, v[126:127]
	v_lshl_add_u64 v[80:81], s[84:85], 0, v[80:81]
	v_lshlrev_b32_e32 v104, 16, v116
	v_and_b32_e32 v105, 0xffff0000, v116
	v_lshlrev_b32_e32 v106, 16, v120
	v_and_b32_e32 v107, 0xffff0000, v120
	v_lshlrev_b32_e32 v108, 16, v117
	v_and_b32_e32 v109, 0xffff0000, v117
	v_lshlrev_b32_e32 v110, 16, v121
	v_and_b32_e32 v111, 0xffff0000, v121
	v_lshl_add_u64 v[126:127], v[80:81], 0, v[112:113]
	v_pk_fma_f32 v[218:219], v[94:95], v[100:101], v[102:103]
	v_pk_fma_f32 v[216:217], v[92:93], v[96:97], v[98:99]
	s_waitcnt vmcnt(0)
	v_lshlrev_b32_e32 v116, 16, v152
	v_and_b32_e32 v117, 0xffff0000, v152
	v_lshlrev_b32_e32 v120, 16, v153
	v_and_b32_e32 v121, 0xffff0000, v153
	v_lshlrev_b32_e32 v142, 16, v124
	v_and_b32_e32 v143, 0xffff0000, v124
	v_pk_fma_f32 v[222:223], v[90:91], v[108:109], v[110:111]
	v_pk_fma_f32 v[220:221], v[88:89], v[104:105], v[106:107]
	v_lshlrev_b32_e32 v152, 16, v154
	v_and_b32_e32 v153, 0xffff0000, v154
	v_lshlrev_b32_e32 v124, 16, v125
	v_and_b32_e32 v125, 0xffff0000, v125
	v_lshlrev_b32_e32 v154, 16, v155
	v_and_b32_e32 v155, 0xffff0000, v155
	s_nop 1
	v_pk_fma_f32 v[226:227], v[86:87], v[118:119], v[120:121]
	v_pk_fma_f32 v[224:225], v[84:85], v[114:115], v[116:117]
	v_or_b32_e32 v114, 48, v140
	v_ashrrev_i32_e32 v115, 31, v114
	s_nop 0
	v_pk_fma_f32 v[230:231], v[156:157], v[124:125], v[154:155]
	v_pk_fma_f32 v[228:229], v[122:123], v[142:143], v[152:153]
	s_nop 1
	v_permlane16_swap_b32_e32 v216, v220
	v_permlane16_swap_b32_e32 v217, v221
	v_permlane16_swap_b32_e32 v218, v222
	v_permlane16_swap_b32_e32 v219, v223
	v_permlane16_swap_b32_e32 v224, v228
	v_permlane16_swap_b32_e32 v225, v229
	v_permlane16_swap_b32_e32 v226, v230
	v_permlane16_swap_b32_e32 v227, v231
	v_permlane32_swap_b32_e32 v216, v224
	v_permlane32_swap_b32_e32 v217, v225
	v_permlane32_swap_b32_e32 v218, v226
	v_permlane32_swap_b32_e32 v219, v227
	v_permlane32_swap_b32_e32 v220, v228
	v_permlane32_swap_b32_e32 v221, v229
	v_permlane32_swap_b32_e32 v222, v230
	v_permlane32_swap_b32_e32 v223, v231
	v_lshl_add_u64 v[234:235], v[126:127], 0, v[232:233]
	global_store_dwordx4 v[234:235], v[216:219], off
	global_store_dwordx4 v[234:235], v[220:223], off offset:64
	global_store_dwordx4 v[234:235], v[224:227], off offset:128
	global_store_dwordx4 v[234:235], v[228:231], off offset:192
	s_nop 1
	v_lshlrev_b64 v[80:81], 6, v[114:115]
	v_lshl_add_u64 v[96:97], s[6:7], 0, v[80:81]
	v_lshlrev_b64 v[96:97], 11, v[114:115]
	v_lshl_add_u64 v[98:99], s[8:9], 0, v[96:97]
	v_lshl_add_u64 v[104:105], v[98:99], 0, v[138:139]
	v_lshl_add_u64 v[100:101], s[0:1], 0, v[96:97]
	global_load_dwordx4 v[96:99], v[104:105], off
	v_lshl_add_u64 v[108:109], v[100:101], 0, v[138:139]
	global_load_dwordx4 v[100:103], v[108:109], off
	s_nop 0
	global_load_dwordx4 v[104:107], v[104:105], off offset:16
	s_nop 0
	global_load_dwordx4 v[108:111], v[108:109], off offset:16
	s_waitcnt vmcnt(7)
	s_waitcnt vmcnt(6)
	s_waitcnt vmcnt(5)
	s_waitcnt vmcnt(4)
	s_waitcnt vmcnt(3)
	v_lshlrev_b32_e32 v84, 16, v97
	v_and_b32_e32 v85, 0xffff0000, v97
	v_fmamk_f32 v80, v211, 0x3a800000, v150
	s_waitcnt vmcnt(1)
	v_and_b32_e32 v97, 0xffff0000, v104
	v_lshlrev_b32_e32 v82, 16, v100
	v_rsq_f32_e32 v80, v80
	v_and_b32_e32 v83, 0xffff0000, v100
	v_lshlrev_b32_e32 v86, 16, v101
	v_and_b32_e32 v87, 0xffff0000, v101
	v_mul_f32_e32 v117, 0xbfb8aa3b, v80
	v_mul_f32_e32 v64, v64, v117
	v_exp_f32_e32 v64, v64
	v_mul_f32_e32 v65, v65, v117
	v_exp_f32_e32 v65, v65
	v_mul_f32_e32 v76, v76, v117
	v_add_f32_e32 v64, 1.0, v64
	v_mul_f32_e32 v77, v77, v117
	v_lshlrev_b32_e32 v80, 16, v96
	v_and_b32_e32 v81, 0xffff0000, v96
	v_mul_f32_e32 v78, v78, v117
	v_mul_f32_e32 v79, v79, v117
	v_lshlrev_b32_e32 v96, 16, v104
	v_rcp_f32_e32 v104, v64
	v_add_f32_e32 v64, 1.0, v65
	v_exp_f32_e32 v76, v76
	v_exp_f32_e32 v77, v77
	v_exp_f32_e32 v78, v78
	v_exp_f32_e32 v79, v79
	v_mul_f32_e32 v72, v72, v117
	v_mul_f32_e32 v73, v73, v117
	v_mul_f32_e32 v74, v74, v117
	v_mul_f32_e32 v75, v75, v117
	v_lshlrev_b32_e32 v100, 16, v105
	v_and_b32_e32 v101, 0xffff0000, v105
	v_rcp_f32_e32 v105, v64
	v_mul_f32_e32 v64, v66, v117
	v_exp_f32_e32 v72, v72
	v_exp_f32_e32 v73, v73
	v_exp_f32_e32 v74, v74
	v_exp_f32_e32 v75, v75
	v_mul_f32_e32 v68, v68, v117
	v_mul_f32_e32 v69, v69, v117
	v_mul_f32_e32 v70, v70, v117
	v_mul_f32_e32 v71, v71, v117
	v_exp_f32_e32 v64, v64
	v_mul_f32_e32 v65, v67, v117
	v_exp_f32_e32 v68, v68
	v_exp_f32_e32 v69, v69
	v_exp_f32_e32 v70, v70
	v_exp_f32_e32 v71, v71
	v_exp_f32_e32 v65, v65
	v_add_f32_e32 v76, 1.0, v76
	v_add_f32_e32 v77, 1.0, v77
	v_add_f32_e32 v78, 1.0, v78
	v_add_f32_e32 v79, 1.0, v79
	v_rcp_f32_e32 v76, v76
	v_rcp_f32_e32 v77, v77
	v_rcp_f32_e32 v78, v78
	v_rcp_f32_e32 v79, v79
	v_add_f32_e32 v72, 1.0, v72
	v_add_f32_e32 v73, 1.0, v73
	v_add_f32_e32 v74, 1.0, v74
	v_add_f32_e32 v75, 1.0, v75
	v_add_f32_e32 v64, 1.0, v64
	v_rcp_f32_e32 v72, v72
	v_rcp_f32_e32 v73, v73
	v_rcp_f32_e32 v74, v74
	v_rcp_f32_e32 v75, v75
	v_add_f32_e32 v68, 1.0, v68
	v_add_f32_e32 v69, 1.0, v69
	v_add_f32_e32 v70, 1.0, v70
	v_add_f32_e32 v71, 1.0, v71
	v_rcp_f32_e32 v118, v64
	v_add_f32_e32 v64, 1.0, v65
	v_rcp_f32_e32 v68, v68
	v_rcp_f32_e32 v69, v69
	v_rcp_f32_e32 v70, v70
	v_rcp_f32_e32 v71, v71
	v_rcp_f32_e32 v119, v64
	v_lshlrev_b64 v[64:65], 12, v[114:115]
	v_lshl_add_u64 v[64:65], s[84:85], 0, v[64:65]
	v_lshlrev_b32_e32 v88, 16, v98
	v_and_b32_e32 v89, 0xffff0000, v98
	v_lshlrev_b32_e32 v90, 16, v102
	v_and_b32_e32 v91, 0xffff0000, v102
	v_lshlrev_b32_e32 v92, 16, v99
	v_and_b32_e32 v93, 0xffff0000, v99
	v_lshlrev_b32_e32 v94, 16, v103
	v_and_b32_e32 v95, 0xffff0000, v103
	v_lshl_add_u64 v[114:115], v[64:65], 0, v[112:113]
	v_pk_fma_f32 v[218:219], v[78:79], v[84:85], v[86:87]
	v_pk_fma_f32 v[216:217], v[76:77], v[80:81], v[82:83]
	s_waitcnt vmcnt(0)
	v_lshlrev_b32_e32 v98, 16, v108
	v_and_b32_e32 v99, 0xffff0000, v108
	v_lshlrev_b32_e32 v102, 16, v109
	v_and_b32_e32 v103, 0xffff0000, v109
	v_lshlrev_b32_e32 v108, 16, v106
	v_and_b32_e32 v109, 0xffff0000, v106
	v_pk_fma_f32 v[222:223], v[74:75], v[92:93], v[94:95]
	v_pk_fma_f32 v[220:221], v[72:73], v[88:89], v[90:91]
	v_lshlrev_b32_e32 v116, 16, v110
	v_and_b32_e32 v117, 0xffff0000, v110
	v_lshlrev_b32_e32 v106, 16, v107
	v_and_b32_e32 v107, 0xffff0000, v107
	v_lshlrev_b32_e32 v110, 16, v111
	v_and_b32_e32 v111, 0xffff0000, v111
	s_nop 1
	v_pk_fma_f32 v[226:227], v[70:71], v[100:101], v[102:103]
	v_pk_fma_f32 v[224:225], v[68:69], v[96:97], v[98:99]
	v_add_u32_e32 v96, 0x80, v140
	v_ashrrev_i32_e32 v97, 31, v96
	s_nop 0
	v_pk_fma_f32 v[230:231], v[118:119], v[106:107], v[110:111]
	v_pk_fma_f32 v[228:229], v[104:105], v[108:109], v[116:117]
	s_nop 1
	v_permlane16_swap_b32_e32 v216, v220
	v_permlane16_swap_b32_e32 v217, v221
	v_permlane16_swap_b32_e32 v218, v222
	v_permlane16_swap_b32_e32 v219, v223
	v_permlane16_swap_b32_e32 v224, v228
	v_permlane16_swap_b32_e32 v225, v229
	v_permlane16_swap_b32_e32 v226, v230
	v_permlane16_swap_b32_e32 v227, v231
	v_permlane32_swap_b32_e32 v216, v224
	v_permlane32_swap_b32_e32 v217, v225
	v_permlane32_swap_b32_e32 v218, v226
	v_permlane32_swap_b32_e32 v219, v227
	v_permlane32_swap_b32_e32 v220, v228
	v_permlane32_swap_b32_e32 v221, v229
	v_permlane32_swap_b32_e32 v222, v230
	v_permlane32_swap_b32_e32 v223, v231
	v_lshl_add_u64 v[234:235], v[114:115], 0, v[232:233]
	global_store_dwordx4 v[234:235], v[216:219], off
	global_store_dwordx4 v[234:235], v[220:223], off offset:64
	global_store_dwordx4 v[234:235], v[224:227], off offset:128
	global_store_dwordx4 v[234:235], v[228:231], off offset:192
	s_nop 1
	v_lshlrev_b64 v[64:65], 6, v[96:97]
	v_lshl_add_u64 v[80:81], s[6:7], 0, v[64:65]
	v_lshlrev_b64 v[80:81], 11, v[96:97]
	v_lshl_add_u64 v[82:83], s[8:9], 0, v[80:81]
	v_lshl_add_u64 v[98:99], v[82:83], 0, v[138:139]
	v_lshl_add_u64 v[84:85], s[0:1], 0, v[80:81]
	global_load_dwordx4 v[80:83], v[98:99], off
	v_lshl_add_u64 v[100:101], v[84:85], 0, v[138:139]
	global_load_dwordx4 v[84:87], v[100:101], off
	global_load_dwordx4 v[88:91], v[98:99], off offset:16
	global_load_dwordx4 v[92:95], v[100:101], off offset:16
	s_waitcnt vmcnt(7)
	s_waitcnt vmcnt(6)
	s_waitcnt vmcnt(5)
	s_waitcnt vmcnt(4)
	s_waitcnt vmcnt(3)
	v_lshlrev_b32_e32 v68, 16, v81
	v_and_b32_e32 v69, 0xffff0000, v81
	v_fmamk_f32 v64, v212, 0x3a800000, v150
	s_waitcnt vmcnt(1)
	v_and_b32_e32 v81, 0xffff0000, v88
	v_lshlrev_b32_e32 v66, 16, v84
	v_rsq_f32_e32 v64, v64
	v_and_b32_e32 v67, 0xffff0000, v84
	v_lshlrev_b32_e32 v70, 16, v85
	v_and_b32_e32 v71, 0xffff0000, v85
	v_mul_f32_e32 v99, 0xbfb8aa3b, v64
	v_mul_f32_e32 v48, v48, v99
	v_exp_f32_e32 v48, v48
	v_mul_f32_e32 v49, v49, v99
	v_exp_f32_e32 v49, v49
	v_mul_f32_e32 v60, v60, v99
	v_add_f32_e32 v48, 1.0, v48
	v_mul_f32_e32 v61, v61, v99
	v_lshlrev_b32_e32 v64, 16, v80
	v_and_b32_e32 v65, 0xffff0000, v80
	v_mul_f32_e32 v62, v62, v99
	v_mul_f32_e32 v63, v63, v99
	v_lshlrev_b32_e32 v80, 16, v88
	v_rcp_f32_e32 v88, v48
	v_add_f32_e32 v48, 1.0, v49
	v_exp_f32_e32 v60, v60
	v_exp_f32_e32 v61, v61
	v_exp_f32_e32 v62, v62
	v_exp_f32_e32 v63, v63
	v_mul_f32_e32 v56, v56, v99
	v_mul_f32_e32 v57, v57, v99
	v_mul_f32_e32 v58, v58, v99
	v_mul_f32_e32 v59, v59, v99
	v_lshlrev_b32_e32 v84, 16, v89
	v_and_b32_e32 v85, 0xffff0000, v89
	v_rcp_f32_e32 v89, v48
	v_mul_f32_e32 v48, v50, v99
	v_exp_f32_e32 v56, v56
	v_exp_f32_e32 v57, v57
	v_exp_f32_e32 v58, v58
	v_exp_f32_e32 v59, v59
	v_mul_f32_e32 v52, v52, v99
	v_mul_f32_e32 v53, v53, v99
	v_mul_f32_e32 v54, v54, v99
	v_mul_f32_e32 v55, v55, v99
	v_exp_f32_e32 v48, v48
	v_mul_f32_e32 v49, v51, v99
	v_exp_f32_e32 v52, v52
	v_exp_f32_e32 v53, v53
	v_exp_f32_e32 v54, v54
	v_exp_f32_e32 v55, v55
	v_exp_f32_e32 v49, v49
	v_add_f32_e32 v60, 1.0, v60
	v_add_f32_e32 v61, 1.0, v61
	v_add_f32_e32 v62, 1.0, v62
	v_add_f32_e32 v63, 1.0, v63
	v_rcp_f32_e32 v60, v60
	v_rcp_f32_e32 v61, v61
	v_rcp_f32_e32 v62, v62
	v_rcp_f32_e32 v63, v63
	v_add_f32_e32 v56, 1.0, v56
	v_add_f32_e32 v57, 1.0, v57
	v_add_f32_e32 v58, 1.0, v58
	v_add_f32_e32 v59, 1.0, v59
	v_add_f32_e32 v48, 1.0, v48
	v_rcp_f32_e32 v56, v56
	v_rcp_f32_e32 v57, v57
	v_rcp_f32_e32 v58, v58
	v_rcp_f32_e32 v59, v59
	v_add_f32_e32 v52, 1.0, v52
	v_add_f32_e32 v53, 1.0, v53
	v_add_f32_e32 v54, 1.0, v54
	v_add_f32_e32 v55, 1.0, v55
	v_rcp_f32_e32 v100, v48
	v_add_f32_e32 v48, 1.0, v49
	v_rcp_f32_e32 v52, v52
	v_rcp_f32_e32 v53, v53
	v_rcp_f32_e32 v54, v54
	v_rcp_f32_e32 v55, v55
	v_rcp_f32_e32 v101, v48
	v_lshlrev_b64 v[48:49], 12, v[96:97]
	v_lshl_add_u64 v[48:49], s[84:85], 0, v[48:49]
	v_lshlrev_b32_e32 v72, 16, v82
	v_and_b32_e32 v73, 0xffff0000, v82
	v_lshlrev_b32_e32 v74, 16, v86
	v_and_b32_e32 v75, 0xffff0000, v86
	v_lshlrev_b32_e32 v76, 16, v83
	v_and_b32_e32 v77, 0xffff0000, v83
	v_lshlrev_b32_e32 v78, 16, v87
	v_and_b32_e32 v79, 0xffff0000, v87
	v_lshl_add_u64 v[96:97], v[48:49], 0, v[112:113]
	v_pk_fma_f32 v[218:219], v[62:63], v[68:69], v[70:71]
	v_pk_fma_f32 v[216:217], v[60:61], v[64:65], v[66:67]
	s_waitcnt vmcnt(0)
	v_lshlrev_b32_e32 v82, 16, v92
	v_and_b32_e32 v83, 0xffff0000, v92
	v_lshlrev_b32_e32 v86, 16, v93
	v_and_b32_e32 v87, 0xffff0000, v93
	v_lshlrev_b32_e32 v92, 16, v90
	v_and_b32_e32 v93, 0xffff0000, v90
	v_pk_fma_f32 v[222:223], v[58:59], v[76:77], v[78:79]
	v_pk_fma_f32 v[220:221], v[56:57], v[72:73], v[74:75]
	v_lshlrev_b32_e32 v98, 16, v94
	v_and_b32_e32 v99, 0xffff0000, v94
	v_lshlrev_b32_e32 v90, 16, v91
	v_and_b32_e32 v91, 0xffff0000, v91
	v_lshlrev_b32_e32 v94, 16, v95
	v_and_b32_e32 v95, 0xffff0000, v95
	s_nop 1
	v_pk_fma_f32 v[226:227], v[54:55], v[84:85], v[86:87]
	v_pk_fma_f32 v[224:225], v[52:53], v[80:81], v[82:83]
	v_add_u32_e32 v80, 0x90, v140
	v_ashrrev_i32_e32 v81, 31, v80
	s_nop 0
	v_pk_fma_f32 v[230:231], v[100:101], v[90:91], v[94:95]
	v_pk_fma_f32 v[228:229], v[88:89], v[92:93], v[98:99]
	s_nop 1
	v_permlane16_swap_b32_e32 v216, v220
	v_permlane16_swap_b32_e32 v217, v221
	v_permlane16_swap_b32_e32 v218, v222
	v_permlane16_swap_b32_e32 v219, v223
	v_permlane16_swap_b32_e32 v224, v228
	v_permlane16_swap_b32_e32 v225, v229
	v_permlane16_swap_b32_e32 v226, v230
	v_permlane16_swap_b32_e32 v227, v231
	v_permlane32_swap_b32_e32 v216, v224
	v_permlane32_swap_b32_e32 v217, v225
	v_permlane32_swap_b32_e32 v218, v226
	v_permlane32_swap_b32_e32 v219, v227
	v_permlane32_swap_b32_e32 v220, v228
	v_permlane32_swap_b32_e32 v221, v229
	v_permlane32_swap_b32_e32 v222, v230
	v_permlane32_swap_b32_e32 v223, v231
	v_lshl_add_u64 v[234:235], v[96:97], 0, v[232:233]
	global_store_dwordx4 v[234:235], v[216:219], off
	global_store_dwordx4 v[234:235], v[220:223], off offset:64
	global_store_dwordx4 v[234:235], v[224:227], off offset:128
	global_store_dwordx4 v[234:235], v[228:231], off offset:192
	s_nop 1
	v_lshlrev_b64 v[48:49], 6, v[80:81]
	v_lshl_add_u64 v[64:65], s[6:7], 0, v[48:49]
	v_lshlrev_b64 v[64:65], 11, v[80:81]
	v_lshl_add_u64 v[66:67], s[8:9], 0, v[64:65]
	v_lshl_add_u64 v[82:83], v[66:67], 0, v[138:139]
	v_lshl_add_u64 v[68:69], s[0:1], 0, v[64:65]
	global_load_dwordx4 v[64:67], v[82:83], off
	v_lshl_add_u64 v[84:85], v[68:69], 0, v[138:139]
	global_load_dwordx4 v[68:71], v[84:85], off
	global_load_dwordx4 v[72:75], v[82:83], off offset:16
	global_load_dwordx4 v[76:79], v[84:85], off offset:16
	s_waitcnt vmcnt(7)
	s_waitcnt vmcnt(6)
	s_waitcnt vmcnt(5)
	s_waitcnt vmcnt(4)
	s_waitcnt vmcnt(3)
	v_lshlrev_b32_e32 v52, 16, v65
	v_and_b32_e32 v53, 0xffff0000, v65
	v_fmamk_f32 v48, v213, 0x3a800000, v150
	s_waitcnt vmcnt(1)
	v_and_b32_e32 v65, 0xffff0000, v72
	v_lshlrev_b32_e32 v50, 16, v68
	v_rsq_f32_e32 v48, v48
	v_and_b32_e32 v51, 0xffff0000, v68
	v_lshlrev_b32_e32 v54, 16, v69
	v_and_b32_e32 v55, 0xffff0000, v69
	v_mul_f32_e32 v83, 0xbfb8aa3b, v48
	v_mul_f32_e32 v32, v32, v83
	v_exp_f32_e32 v32, v32
	v_mul_f32_e32 v33, v33, v83
	v_exp_f32_e32 v33, v33
	v_mul_f32_e32 v44, v44, v83
	v_add_f32_e32 v32, 1.0, v32
	v_mul_f32_e32 v45, v45, v83
	v_lshlrev_b32_e32 v48, 16, v64
	v_and_b32_e32 v49, 0xffff0000, v64
	v_mul_f32_e32 v46, v46, v83
	v_mul_f32_e32 v47, v47, v83
	v_lshlrev_b32_e32 v64, 16, v72
	v_rcp_f32_e32 v72, v32
	v_add_f32_e32 v32, 1.0, v33
	v_exp_f32_e32 v44, v44
	v_exp_f32_e32 v45, v45
	v_exp_f32_e32 v46, v46
	v_exp_f32_e32 v47, v47
	v_mul_f32_e32 v40, v40, v83
	v_mul_f32_e32 v41, v41, v83
	v_mul_f32_e32 v42, v42, v83
	v_mul_f32_e32 v43, v43, v83
	v_lshlrev_b32_e32 v68, 16, v73
	v_and_b32_e32 v69, 0xffff0000, v73
	v_rcp_f32_e32 v73, v32
	v_mul_f32_e32 v32, v34, v83
	v_exp_f32_e32 v40, v40
	v_exp_f32_e32 v41, v41
	v_exp_f32_e32 v42, v42
	v_exp_f32_e32 v43, v43
	v_mul_f32_e32 v36, v36, v83
	v_mul_f32_e32 v37, v37, v83
	v_mul_f32_e32 v38, v38, v83
	v_mul_f32_e32 v39, v39, v83
	v_exp_f32_e32 v32, v32
	v_mul_f32_e32 v33, v35, v83
	v_exp_f32_e32 v36, v36
	v_exp_f32_e32 v37, v37
	v_exp_f32_e32 v38, v38
	v_exp_f32_e32 v39, v39
	v_exp_f32_e32 v33, v33
	v_add_f32_e32 v44, 1.0, v44
	v_add_f32_e32 v45, 1.0, v45
	v_add_f32_e32 v46, 1.0, v46
	v_add_f32_e32 v47, 1.0, v47
	v_rcp_f32_e32 v44, v44
	v_rcp_f32_e32 v45, v45
	v_rcp_f32_e32 v46, v46
	v_rcp_f32_e32 v47, v47
	v_add_f32_e32 v40, 1.0, v40
	v_add_f32_e32 v41, 1.0, v41
	v_add_f32_e32 v42, 1.0, v42
	v_add_f32_e32 v43, 1.0, v43
	v_add_f32_e32 v32, 1.0, v32
	v_rcp_f32_e32 v40, v40
	v_rcp_f32_e32 v41, v41
	v_rcp_f32_e32 v42, v42
	v_rcp_f32_e32 v43, v43
	v_add_f32_e32 v36, 1.0, v36
	v_add_f32_e32 v37, 1.0, v37
	v_add_f32_e32 v38, 1.0, v38
	v_add_f32_e32 v39, 1.0, v39
	v_rcp_f32_e32 v84, v32
	v_add_f32_e32 v32, 1.0, v33
	v_rcp_f32_e32 v36, v36
	v_rcp_f32_e32 v37, v37
	v_rcp_f32_e32 v38, v38
	v_rcp_f32_e32 v39, v39
	v_rcp_f32_e32 v85, v32
	v_lshlrev_b64 v[32:33], 12, v[80:81]
	v_lshl_add_u64 v[32:33], s[84:85], 0, v[32:33]
	v_lshlrev_b32_e32 v56, 16, v66
	v_and_b32_e32 v57, 0xffff0000, v66
	v_lshlrev_b32_e32 v58, 16, v70
	v_and_b32_e32 v59, 0xffff0000, v70
	v_lshlrev_b32_e32 v60, 16, v67
	v_and_b32_e32 v61, 0xffff0000, v67
	v_lshlrev_b32_e32 v62, 16, v71
	v_and_b32_e32 v63, 0xffff0000, v71
	v_lshl_add_u64 v[80:81], v[32:33], 0, v[112:113]
	v_pk_fma_f32 v[218:219], v[46:47], v[52:53], v[54:55]
	v_pk_fma_f32 v[216:217], v[44:45], v[48:49], v[50:51]
	s_waitcnt vmcnt(0)
	v_lshlrev_b32_e32 v66, 16, v76
	v_and_b32_e32 v67, 0xffff0000, v76
	v_lshlrev_b32_e32 v70, 16, v77
	v_and_b32_e32 v71, 0xffff0000, v77
	v_lshlrev_b32_e32 v76, 16, v74
	v_and_b32_e32 v77, 0xffff0000, v74
	v_pk_fma_f32 v[222:223], v[42:43], v[60:61], v[62:63]
	v_pk_fma_f32 v[220:221], v[40:41], v[56:57], v[58:59]
	v_lshlrev_b32_e32 v82, 16, v78
	v_and_b32_e32 v83, 0xffff0000, v78
	v_lshlrev_b32_e32 v74, 16, v75
	v_and_b32_e32 v75, 0xffff0000, v75
	v_lshlrev_b32_e32 v78, 16, v79
	v_and_b32_e32 v79, 0xffff0000, v79
	s_nop 1
	v_pk_fma_f32 v[226:227], v[38:39], v[68:69], v[70:71]
	v_pk_fma_f32 v[224:225], v[36:37], v[64:65], v[66:67]
	v_add_u32_e32 v64, 0xa0, v140
	v_ashrrev_i32_e32 v65, 31, v64
	s_nop 0
	v_pk_fma_f32 v[230:231], v[84:85], v[74:75], v[78:79]
	v_pk_fma_f32 v[228:229], v[72:73], v[76:77], v[82:83]
	s_nop 1
	v_permlane16_swap_b32_e32 v216, v220
	v_permlane16_swap_b32_e32 v217, v221
	v_permlane16_swap_b32_e32 v218, v222
	v_permlane16_swap_b32_e32 v219, v223
	v_permlane16_swap_b32_e32 v224, v228
	v_permlane16_swap_b32_e32 v225, v229
	v_permlane16_swap_b32_e32 v226, v230
	v_permlane16_swap_b32_e32 v227, v231
	v_permlane32_swap_b32_e32 v216, v224
	v_permlane32_swap_b32_e32 v217, v225
	v_permlane32_swap_b32_e32 v218, v226
	v_permlane32_swap_b32_e32 v219, v227
	v_permlane32_swap_b32_e32 v220, v228
	v_permlane32_swap_b32_e32 v221, v229
	v_permlane32_swap_b32_e32 v222, v230
	v_permlane32_swap_b32_e32 v223, v231
	v_lshl_add_u64 v[234:235], v[80:81], 0, v[232:233]
	global_store_dwordx4 v[234:235], v[216:219], off
	global_store_dwordx4 v[234:235], v[220:223], off offset:64
	global_store_dwordx4 v[234:235], v[224:227], off offset:128
	global_store_dwordx4 v[234:235], v[228:231], off offset:192
	s_nop 1
	v_lshlrev_b64 v[32:33], 6, v[64:65]
	v_lshl_add_u64 v[48:49], s[6:7], 0, v[32:33]
	v_lshlrev_b64 v[48:49], 11, v[64:65]
	v_lshl_add_u64 v[50:51], s[8:9], 0, v[48:49]
	v_lshl_add_u64 v[66:67], v[50:51], 0, v[138:139]
	v_lshl_add_u64 v[52:53], s[0:1], 0, v[48:49]
	global_load_dwordx4 v[48:51], v[66:67], off
	v_lshl_add_u64 v[68:69], v[52:53], 0, v[138:139]
	global_load_dwordx4 v[52:55], v[68:69], off
	global_load_dwordx4 v[56:59], v[66:67], off offset:16
	global_load_dwordx4 v[60:63], v[68:69], off offset:16
	s_waitcnt vmcnt(7)
	s_waitcnt vmcnt(6)
	s_waitcnt vmcnt(5)
	s_waitcnt vmcnt(4)
	s_waitcnt vmcnt(3)
	v_lshlrev_b32_e32 v36, 16, v49
	v_and_b32_e32 v37, 0xffff0000, v49
	v_fmamk_f32 v32, v214, 0x3a800000, v150
	s_waitcnt vmcnt(1)
	v_and_b32_e32 v49, 0xffff0000, v56
	v_lshlrev_b32_e32 v34, 16, v52
	v_rsq_f32_e32 v32, v32
	v_and_b32_e32 v35, 0xffff0000, v52
	v_lshlrev_b32_e32 v38, 16, v53
	v_and_b32_e32 v39, 0xffff0000, v53
	v_mul_f32_e32 v67, 0xbfb8aa3b, v32
	v_mul_f32_e32 v16, v16, v67
	v_exp_f32_e32 v16, v16
	v_mul_f32_e32 v17, v17, v67
	v_exp_f32_e32 v17, v17
	v_mul_f32_e32 v28, v28, v67
	v_add_f32_e32 v16, 1.0, v16
	v_mul_f32_e32 v29, v29, v67
	v_lshlrev_b32_e32 v32, 16, v48
	v_and_b32_e32 v33, 0xffff0000, v48
	v_mul_f32_e32 v30, v30, v67
	v_mul_f32_e32 v31, v31, v67
	v_lshlrev_b32_e32 v48, 16, v56
	v_rcp_f32_e32 v56, v16
	v_add_f32_e32 v16, 1.0, v17
	v_exp_f32_e32 v28, v28
	v_exp_f32_e32 v29, v29
	v_exp_f32_e32 v30, v30
	v_exp_f32_e32 v31, v31
	v_mul_f32_e32 v24, v24, v67
	v_mul_f32_e32 v25, v25, v67
	v_mul_f32_e32 v26, v26, v67
	v_mul_f32_e32 v27, v27, v67
	v_lshlrev_b32_e32 v52, 16, v57
	v_and_b32_e32 v53, 0xffff0000, v57
	v_rcp_f32_e32 v57, v16
	v_mul_f32_e32 v16, v18, v67
	v_exp_f32_e32 v24, v24
	v_exp_f32_e32 v25, v25
	v_exp_f32_e32 v26, v26
	v_exp_f32_e32 v27, v27
	v_mul_f32_e32 v20, v20, v67
	v_mul_f32_e32 v21, v21, v67
	v_mul_f32_e32 v22, v22, v67
	v_mul_f32_e32 v23, v23, v67
	v_exp_f32_e32 v16, v16
	v_mul_f32_e32 v17, v19, v67
	v_exp_f32_e32 v20, v20
	v_exp_f32_e32 v21, v21
	v_exp_f32_e32 v22, v22
	v_exp_f32_e32 v23, v23
	v_exp_f32_e32 v17, v17
	v_add_f32_e32 v28, 1.0, v28
	v_add_f32_e32 v29, 1.0, v29
	v_add_f32_e32 v30, 1.0, v30
	v_add_f32_e32 v31, 1.0, v31
	v_rcp_f32_e32 v28, v28
	v_rcp_f32_e32 v29, v29
	v_rcp_f32_e32 v30, v30
	v_rcp_f32_e32 v31, v31
	v_add_f32_e32 v24, 1.0, v24
	v_add_f32_e32 v25, 1.0, v25
	v_add_f32_e32 v26, 1.0, v26
	v_add_f32_e32 v27, 1.0, v27
	v_add_f32_e32 v16, 1.0, v16
	v_rcp_f32_e32 v24, v24
	v_rcp_f32_e32 v25, v25
	v_rcp_f32_e32 v26, v26
	v_rcp_f32_e32 v27, v27
	v_add_f32_e32 v20, 1.0, v20
	v_add_f32_e32 v21, 1.0, v21
	v_add_f32_e32 v22, 1.0, v22
	v_add_f32_e32 v23, 1.0, v23
	v_rcp_f32_e32 v68, v16
	v_add_f32_e32 v16, 1.0, v17
	v_rcp_f32_e32 v20, v20
	v_rcp_f32_e32 v21, v21
	v_rcp_f32_e32 v22, v22
	v_rcp_f32_e32 v23, v23
	v_rcp_f32_e32 v69, v16
	v_lshlrev_b64 v[16:17], 12, v[64:65]
	v_lshl_add_u64 v[16:17], s[84:85], 0, v[16:17]
	v_lshlrev_b32_e32 v40, 16, v50
	v_and_b32_e32 v41, 0xffff0000, v50
	v_lshlrev_b32_e32 v42, 16, v54
	v_and_b32_e32 v43, 0xffff0000, v54
	v_lshlrev_b32_e32 v44, 16, v51
	v_and_b32_e32 v45, 0xffff0000, v51
	v_lshlrev_b32_e32 v46, 16, v55
	v_and_b32_e32 v47, 0xffff0000, v55
	v_lshl_add_u64 v[64:65], v[16:17], 0, v[112:113]
	v_pk_fma_f32 v[218:219], v[30:31], v[36:37], v[38:39]
	v_pk_fma_f32 v[216:217], v[28:29], v[32:33], v[34:35]
	s_waitcnt vmcnt(0)
	v_lshlrev_b32_e32 v50, 16, v60
	v_and_b32_e32 v51, 0xffff0000, v60
	v_lshlrev_b32_e32 v54, 16, v61
	v_and_b32_e32 v55, 0xffff0000, v61
	v_lshlrev_b32_e32 v60, 16, v58
	v_and_b32_e32 v61, 0xffff0000, v58
	v_pk_fma_f32 v[222:223], v[26:27], v[44:45], v[46:47]
	v_pk_fma_f32 v[220:221], v[24:25], v[40:41], v[42:43]
	v_lshlrev_b32_e32 v66, 16, v62
	v_and_b32_e32 v67, 0xffff0000, v62
	v_lshlrev_b32_e32 v58, 16, v59
	v_and_b32_e32 v59, 0xffff0000, v59
	v_lshlrev_b32_e32 v62, 16, v63
	v_and_b32_e32 v63, 0xffff0000, v63
	s_nop 1
	v_pk_fma_f32 v[226:227], v[22:23], v[52:53], v[54:55]
	v_pk_fma_f32 v[224:225], v[20:21], v[48:49], v[50:51]
	v_add_u32_e32 v48, 0xb0, v140
	v_ashrrev_i32_e32 v49, 31, v48
	s_nop 0
	v_pk_fma_f32 v[230:231], v[68:69], v[58:59], v[62:63]
	v_pk_fma_f32 v[228:229], v[56:57], v[60:61], v[66:67]
	s_nop 1
	v_permlane16_swap_b32_e32 v216, v220
	v_permlane16_swap_b32_e32 v217, v221
	v_permlane16_swap_b32_e32 v218, v222
	v_permlane16_swap_b32_e32 v219, v223
	v_permlane16_swap_b32_e32 v224, v228
	v_permlane16_swap_b32_e32 v225, v229
	v_permlane16_swap_b32_e32 v226, v230
	v_permlane16_swap_b32_e32 v227, v231
	v_permlane32_swap_b32_e32 v216, v224
	v_permlane32_swap_b32_e32 v217, v225
	v_permlane32_swap_b32_e32 v218, v226
	v_permlane32_swap_b32_e32 v219, v227
	v_permlane32_swap_b32_e32 v220, v228
	v_permlane32_swap_b32_e32 v221, v229
	v_permlane32_swap_b32_e32 v222, v230
	v_permlane32_swap_b32_e32 v223, v231
	v_lshl_add_u64 v[234:235], v[64:65], 0, v[232:233]
	global_store_dwordx4 v[234:235], v[216:219], off
	global_store_dwordx4 v[234:235], v[220:223], off offset:64
	global_store_dwordx4 v[234:235], v[224:227], off offset:128
	global_store_dwordx4 v[234:235], v[228:231], off offset:192
	s_nop 1
	v_lshlrev_b64 v[16:17], 6, v[48:49]
	v_lshl_add_u64 v[32:33], s[6:7], 0, v[16:17]
	v_lshlrev_b64 v[32:33], 11, v[48:49]
	v_lshl_add_u64 v[34:35], s[8:9], 0, v[32:33]
	v_lshl_add_u64 v[50:51], v[34:35], 0, v[138:139]
	v_lshl_add_u64 v[36:37], s[0:1], 0, v[32:33]
	global_load_dwordx4 v[32:35], v[50:51], off
	v_lshl_add_u64 v[52:53], v[36:37], 0, v[138:139]
	global_load_dwordx4 v[36:39], v[52:53], off
	global_load_dwordx4 v[40:43], v[50:51], off offset:16
	global_load_dwordx4 v[44:47], v[52:53], off offset:16
	s_waitcnt vmcnt(7)
	s_waitcnt vmcnt(6)
	s_waitcnt vmcnt(5)
	s_waitcnt vmcnt(4)
	s_waitcnt vmcnt(3)
	v_lshlrev_b32_e32 v20, 16, v33
	v_and_b32_e32 v21, 0xffff0000, v33
	v_fmamk_f32 v16, v215, 0x3a800000, v150
	s_waitcnt vmcnt(1)
	v_and_b32_e32 v33, 0xffff0000, v40
	v_lshlrev_b32_e32 v18, 16, v36
	v_rsq_f32_e32 v16, v16
	v_and_b32_e32 v19, 0xffff0000, v36
	v_lshlrev_b32_e32 v22, 16, v37
	v_and_b32_e32 v23, 0xffff0000, v37
	v_mul_f32_e32 v51, 0xbfb8aa3b, v16
	v_mul_f32_e32 v0, v0, v51
	v_exp_f32_e32 v0, v0
	v_mul_f32_e32 v1, v1, v51
	v_exp_f32_e32 v1, v1
	v_mul_f32_e32 v12, v12, v51
	v_add_f32_e32 v0, 1.0, v0
	v_mul_f32_e32 v13, v13, v51
	v_lshlrev_b32_e32 v16, 16, v32
	v_and_b32_e32 v17, 0xffff0000, v32
	v_mul_f32_e32 v14, v14, v51
	v_mul_f32_e32 v15, v15, v51
	v_lshlrev_b32_e32 v32, 16, v40
	v_rcp_f32_e32 v40, v0
	v_add_f32_e32 v0, 1.0, v1
	v_exp_f32_e32 v12, v12
	v_exp_f32_e32 v13, v13
	v_exp_f32_e32 v14, v14
	v_exp_f32_e32 v15, v15
	v_mul_f32_e32 v8, v8, v51
	v_mul_f32_e32 v9, v9, v51
	v_mul_f32_e32 v10, v10, v51
	v_mul_f32_e32 v11, v11, v51
	v_lshlrev_b32_e32 v36, 16, v41
	v_and_b32_e32 v37, 0xffff0000, v41
	v_rcp_f32_e32 v41, v0
	v_mul_f32_e32 v0, v2, v51
	v_exp_f32_e32 v8, v8
	v_exp_f32_e32 v9, v9
	v_exp_f32_e32 v10, v10
	v_exp_f32_e32 v11, v11
	v_mul_f32_e32 v4, v4, v51
	v_mul_f32_e32 v5, v5, v51
	v_mul_f32_e32 v6, v6, v51
	v_mul_f32_e32 v7, v7, v51
	v_exp_f32_e32 v0, v0
	v_mul_f32_e32 v1, v3, v51
	v_exp_f32_e32 v4, v4
	v_exp_f32_e32 v5, v5
	v_exp_f32_e32 v6, v6
	v_exp_f32_e32 v7, v7
	v_exp_f32_e32 v1, v1
	v_add_f32_e32 v12, 1.0, v12
	v_add_f32_e32 v13, 1.0, v13
	v_add_f32_e32 v14, 1.0, v14
	v_add_f32_e32 v15, 1.0, v15
	v_rcp_f32_e32 v12, v12
	v_rcp_f32_e32 v13, v13
	v_rcp_f32_e32 v14, v14
	v_rcp_f32_e32 v15, v15
	v_add_f32_e32 v8, 1.0, v8
	v_add_f32_e32 v9, 1.0, v9
	v_add_f32_e32 v10, 1.0, v10
	v_add_f32_e32 v11, 1.0, v11
	v_add_f32_e32 v0, 1.0, v0
	v_rcp_f32_e32 v8, v8
	v_rcp_f32_e32 v9, v9
	v_rcp_f32_e32 v10, v10
	v_rcp_f32_e32 v11, v11
	v_add_f32_e32 v4, 1.0, v4
	v_add_f32_e32 v5, 1.0, v5
	v_add_f32_e32 v6, 1.0, v6
	v_add_f32_e32 v7, 1.0, v7
	v_rcp_f32_e32 v52, v0
	v_add_f32_e32 v0, 1.0, v1
	v_rcp_f32_e32 v4, v4
	v_rcp_f32_e32 v5, v5
	v_rcp_f32_e32 v6, v6
	v_rcp_f32_e32 v7, v7
	v_rcp_f32_e32 v53, v0
	v_lshlrev_b64 v[0:1], 12, v[48:49]
	v_lshl_add_u64 v[0:1], s[84:85], 0, v[0:1]
	v_lshlrev_b32_e32 v24, 16, v34
	v_and_b32_e32 v25, 0xffff0000, v34
	v_lshlrev_b32_e32 v26, 16, v38
	v_and_b32_e32 v27, 0xffff0000, v38
	v_lshlrev_b32_e32 v28, 16, v35
	v_and_b32_e32 v29, 0xffff0000, v35
	v_lshlrev_b32_e32 v30, 16, v39
	v_and_b32_e32 v31, 0xffff0000, v39
	v_lshl_add_u64 v[48:49], v[0:1], 0, v[112:113]
	v_pk_fma_f32 v[218:219], v[14:15], v[20:21], v[22:23]
	v_pk_fma_f32 v[216:217], v[12:13], v[16:17], v[18:19]
	s_waitcnt vmcnt(0)
	v_lshlrev_b32_e32 v34, 16, v44
	v_and_b32_e32 v35, 0xffff0000, v44
	v_lshlrev_b32_e32 v38, 16, v45
	v_and_b32_e32 v39, 0xffff0000, v45
	v_lshlrev_b32_e32 v44, 16, v42
	v_and_b32_e32 v45, 0xffff0000, v42
	v_pk_fma_f32 v[222:223], v[10:11], v[28:29], v[30:31]
	v_pk_fma_f32 v[220:221], v[8:9], v[24:25], v[26:27]
	v_lshlrev_b32_e32 v50, 16, v46
	v_and_b32_e32 v51, 0xffff0000, v46
	v_lshlrev_b32_e32 v42, 16, v43
	v_and_b32_e32 v43, 0xffff0000, v43
	v_lshlrev_b32_e32 v46, 16, v47
	v_and_b32_e32 v47, 0xffff0000, v47
	s_nop 1
	v_pk_fma_f32 v[226:227], v[6:7], v[36:37], v[38:39]
	v_pk_fma_f32 v[224:225], v[4:5], v[32:33], v[34:35]
	s_nop 1
	v_pk_fma_f32 v[230:231], v[52:53], v[42:43], v[46:47]
	v_pk_fma_f32 v[228:229], v[40:41], v[44:45], v[50:51]
	s_nop 1
	v_permlane16_swap_b32_e32 v216, v220
	v_permlane16_swap_b32_e32 v217, v221
	v_permlane16_swap_b32_e32 v218, v222
	v_permlane16_swap_b32_e32 v219, v223
	v_permlane16_swap_b32_e32 v224, v228
	v_permlane16_swap_b32_e32 v225, v229
	v_permlane16_swap_b32_e32 v226, v230
	v_permlane16_swap_b32_e32 v227, v231
	v_permlane32_swap_b32_e32 v216, v224
	v_permlane32_swap_b32_e32 v217, v225
	v_permlane32_swap_b32_e32 v218, v226
	v_permlane32_swap_b32_e32 v219, v227
	v_permlane32_swap_b32_e32 v220, v228
	v_permlane32_swap_b32_e32 v221, v229
	v_permlane32_swap_b32_e32 v222, v230
	v_permlane32_swap_b32_e32 v223, v231
	v_lshl_add_u64 v[234:235], v[48:49], 0, v[232:233]
	global_store_dwordx4 v[234:235], v[216:219], off
	global_store_dwordx4 v[234:235], v[220:223], off offset:64
	global_store_dwordx4 v[234:235], v[224:227], off offset:128
	global_store_dwordx4 v[234:235], v[228:231], off offset:192
	s_cbranch_scc1 .LBB0_1643
	s_andn2_b64 vcc, exec, s[4:5]
	s_cbranch_vccnz .LBB0_1642
	s_barrier
	s_branch .LBB0_1642
